# delta long-scan waves at s_setprio 1 (same level as the GEMM MFMA bursts); rwkv unchanged
# baseline (speedup 1.0000x reference)
; __device__ __forceinline__ int tidx() { int t = threadIdx.x; asm volatile("" : "+v"(t)); return t; }
; __device__ __forceinline__ void delta_scan_task(KP p, int l, bool samp, int b, int h, int cgp, float* sm) {
;     const int tid_ = tidx();
;     const int tid = tid_, lane = tid & 63, wid = tid >> 6, cc = lane >> 3, ks = lane & 7;
;     const int L = samp ? 8 : 2048, row0 = samp ? TPROMPT + b * 8 : b * 2048;
;     const int e = cgp * 32 + wid * 8 + cc;
;     const bf16_t* Dq = (const bf16_t*)(p->ws + OFF_DQ); const bf16_t* Dk = (const bf16_t*)(p->ws + OFF_DK); const bf16_t* Dv = (const bf16_t*)(p->ws + OFF_DV);
;     const float* Dsc = (const float*)(p->ws + OFF_DSC);
;     float* oraw = (float*)(p->ws + OFF_Y) + (size_t)NTOK * 512;
;     f32x2 S[8];
;     const size_t sbase = samp ? ((size_t)((l * 128 + b) * 4 + h) * 128) * 128 : ((size_t)((l * 8 + b) * 4 + h) * 128) * 128;
; #pragma unroll
;     for (int j = 0; j < 8; ++j) {
;         S[j] = (f32x2){0.f, 0.f};
;         if (samp) {
;             S[j].x = p->in[I_SDELTA][sbase + (size_t)(ks * 16 + 2 * j) * 128 + e];
;             S[j].y = p->in[I_SDELTA][sbase + (size_t)(ks * 16 + 2 * j + 1) * 128 + e];
;         }
;     }
;     const int sstep = tid >> 4, sc = tid & 15;
;     uint4 pk, pq; unsigned pv; float2 psc;
;     const int ntile = (L + 15) >> 4;
;     auto load_tile = [&](int tile) {
;         const int step = tile * 16 + sstep;
;         if (step < L) {
;             const size_t o = (size_t)(row0 + step) * 512 + h * 128 + sc * 8;
;             pk = *(const uint4*)(Dk + o); pq = *(const uint4*)(Dq + o);
;             pv = *(const unsigned*)(Dv + (size_t)(row0 + step) * 512 + h * 128 + cgp * 32 + sc * 2);
;         }
;         if (tid < 16 && tile * 16 + tid < L) psc = *(const float2*)(Dsc + ((size_t)(row0 + tile * 16 + tid) * 4 + h) * 2);
;     };
;     load_tile(0);
.LBB0_132:
	s_andn2_b64 vcc, exec, s[12:13]
	s_cbranch_vccnz .LBB0_166
	v_readlane_b32 s14, v233, 15
	v_readlane_b32 s15, v233, 16
	s_mov_b64 s[12:13], -1
	s_and_b64 vcc, exec, s[14:15]
	s_cbranch_vccz .LBB0_151
	s_setprio 1
	s_add_u32 s14, s58, 0x25968000
	s_addc_u32 s15, s59, 0
	s_add_u32 s22, s58, 0x26a68000
	v_mov_b32_e32 v48, v192
	s_addc_u32 s23, s59, 0
	s_add_u32 s18, s58, 0x27b68000
	v_ashrrev_i32_e32 v49, 4, v48
	v_and_b32_e32 v10, 15, v48
	s_movk_i32 s2, 0x800
	s_addc_u32 s19, s59, 0
	v_cmp_gt_i32_e32 vcc, s2, v49
	v_lshlrev_b32_e32 v8, 2, v10
	s_and_saveexec_b64 s[24:25], vcc
	s_cbranch_execz .LBB0_136
	v_readlane_b32 s12, v232, 61
	v_readlane_b32 s2, v233, 19
	s_lshl_b32 s86, s2, 1
	s_waitcnt vmcnt(10)
	v_add_u32_e32 v14, s12, v49
	v_ashrrev_i32_e32 v15, 31, v14
	v_lshlrev_b64 v[0:1], 9, v[14:15]
	v_lshl_or_b32 v0, v10, 3, v0
	v_lshlrev_b64 v[14:15], 10, v[14:15]
	v_or_b32_e32 v0, s2, v0
	v_lshl_add_u64 v[14:15], s[18:19], 0, v[14:15]
	v_readlane_b32 s2, v233, 17
	v_lshlrev_b64 v[0:1], 1, v[0:1]
	v_lshl_add_u64 v[14:15], v[14:15], 0, s[86:87]
	s_lshl_b32 s86, s2, 1
	v_lshl_add_u64 v[2:3], s[22:23], 0, v[0:1]
	v_lshl_add_u64 v[0:1], s[14:15], 0, v[0:1]
	v_lshl_add_u64 v[14:15], v[14:15], 0, s[86:87]
	v_mov_b32_e32 v9, v13
	global_load_dwordx4 v[4:7], v[2:3], off
	s_nop 0
	global_load_dwordx4 v[0:3], v[0:1], off
	v_lshl_add_u64 v[14:15], v[14:15], 0, v[8:9]
	global_load_dword v50, v[14:15], off
	v_readlane_b32 s13, v232, 62
	s_waitcnt vmcnt(1)
	v_mov_b32_e32 v20, v1
	v_mov_b32_e32 v21, v2

; __device__ __forceinline__ void delta_scan_task(KP p, int l, bool samp, int b, int h, int cgp, float* sm) {
;     ...
;         for (int s0 = 0; s0 < nst; s0 += 4) {
; #pragma unroll
;             for (int s4 = 0; s4 < 4; ++s4) {
;                 const int s = s0 + s4;
;                 f32x2 k2[8], q2[8];
; #pragma unroll
;                 for (int hh = 0; hh < 4; ++hh) {
;                     const float4 a = *(const float4*)(bufp + s * 128 + ks * 16 + hh * 4);
;                     const float4 c = *(const float4*)(bufp + 2048 + s * 128 + ks * 16 + hh * 4);
;                     k2[2 * hh] = (f32x2){a.x, a.y}; k2[2 * hh + 1] = (f32x2){a.z, a.w};
;                     q2[2 * hh] = (f32x2){c.x, c.y}; q2[2 * hh + 1] = (f32x2){c.z, c.w};
;                 }
;                 const float vv = bufp[4096 + s * 32 + wid * 8 + cc];
;                 const float beta = bufp[4608 + s], alpha = bufp[4624 + s];
;                 f32x2 d0 = S[0] * k2[0], d1v = S[1] * k2[1], d2 = S[2] * k2[2], d3 = S[3] * k2[3];
;                 d0 = S[4] * k2[4] + d0; d1v = S[5] * k2[5] + d1v; d2 = S[6] * k2[6] + d2; d3 = S[7] * k2[7] + d3;
;                 d0 = (d0 + d1v) + (d2 + d3);
;                 const f32x2 al2 = (f32x2){alpha, alpha};
;                 f32x2 sa[8];
; #pragma unroll
;                 for (int j = 0; j < 8; ++j) sa[j] = S[j] * al2;
;                 const float dk = red8(d0.x + d0.y);
;                 const float vn = beta * (vv - alpha * dk);
;                 const f32x2 vn2 = (f32x2){vn, vn};
; #pragma unroll
;                 for (int j = 0; j < 8; ++j) S[j] = k2[j] * vn2 + sa[j];
;                 f32x2 o0 = S[0] * q2[0], o1 = S[1] * q2[1], o2 = S[2] * q2[2], o3 = S[3] * q2[3];
;                 o0 = S[4] * q2[4] + o0; o1 = S[5] * q2[5] + o1; o2 = S[6] * q2[6] + o2; o3 = S[7] * q2[7] + o3;
;                 o0 = (o0 + o1) + (o2 + o3);
;                 const float o = red8(o0.x + o0.y);
;                 oraw[(size_t)(row0 + tile * 16 + s) * 512 + h * 128 + e] = o;
;             }
.LBB0_147:
	v_add_u32_e32 v65, s11, v56
	v_add_u32_e32 v100, s11, v55
	s_add_i32 s2, s11, 0x4800
	v_mov_b32_e32 v234, s2
	s_mov_b32 s12, 0xfffff800
	s_mov_b32 s13, -1
	v_lshl_add_u64 v[28:29], v[26:27], 0, s[12:13]
	ds_read_b128 v[66:69], v65
	ds_read_b128 v[70:73], v65 offset:16
	ds_read_b128 v[74:77], v65 offset:32
	ds_read_b128 v[78:81], v65 offset:48
	ds_read_b128 v[14:17], v234 offset:64
	ds_read_b128 v[8:11], v234
	ds_read_b32 v58, v100
	ds_read_b32 v59, v100 offset:128
	ds_read_b32 v60, v100 offset:256
	ds_read_b32 v61, v100 offset:384
	ds_read_b128 v[82:85], v65 offset:512
	ds_read_b128 v[86:89], v65 offset:528
	ds_read_b128 v[90:93], v65 offset:544
	ds_read_b128 v[94:97], v65 offset:560
	s_waitcnt lgkmcnt(13)
	v_pk_mul_f32 v[62:63], v[30:31], v[66:67]
	v_pk_mul_f32 v[98:99], v[44:45], v[68:69]
	s_waitcnt lgkmcnt(12)
	v_pk_fma_f32 v[62:63], v[38:39], v[70:71], v[62:63]
	v_pk_fma_f32 v[98:99], v[36:37], v[72:73], v[98:99]
	s_waitcnt lgkmcnt(11)
	v_pk_fma_f32 v[62:63], v[34:35], v[74:75], v[62:63]
	v_pk_fma_f32 v[98:99], v[32:33], v[76:77], v[98:99]
	s_waitcnt lgkmcnt(10)
	v_pk_fma_f32 v[62:63], v[40:41], v[78:79], v[62:63]
	v_pk_fma_f32 v[98:99], v[42:43], v[80:81], v[98:99]
	s_nop 0
	v_pk_add_f32 v[62:63], v[62:63], v[98:99]
	ds_read_b128 v[236:239], v65 offset:8192
	ds_read_b128 v[240:243], v65 offset:8208
	ds_read_b128 v[244:247], v65 offset:8224
	ds_read_b128 v[248:251], v65 offset:8240
	v_add_f32_e32 v62, v62, v63
	s_waitcnt lgkmcnt(13)
	v_pk_mul_f32 v[30:31], v[30:31], v[14:15] op_sel_hi:[1,0]
	v_pk_mul_f32 v[44:45], v[44:45], v[14:15] op_sel_hi:[1,0]
	v_add_f32_dpp v62, v62, v62 quad_perm:[1,0,3,2] row_mask:0xf bank_mask:0xf bound_ctrl:1
	v_pk_mul_f32 v[38:39], v[38:39], v[14:15] op_sel_hi:[1,0]
	v_pk_mul_f32 v[36:37], v[36:37], v[14:15] op_sel_hi:[1,0]
	v_add_f32_dpp v62, v62, v62 quad_perm:[2,3,0,1] row_mask:0xf bank_mask:0xf bound_ctrl:1
	v_pk_mul_f32 v[34:35], v[34:35], v[14:15] op_sel_hi:[1,0]
	v_pk_mul_f32 v[32:33], v[32:33], v[14:15] op_sel_hi:[1,0]
	v_add_f32_dpp v62, v62, v62 row_half_mirror row_mask:0xf bank_mask:0xf bound_ctrl:1
	v_pk_mul_f32 v[40:41], v[40:41], v[14:15] op_sel_hi:[1,0]
	v_pk_mul_f32 v[42:43], v[42:43], v[14:15] op_sel_hi:[1,0]
	s_waitcnt lgkmcnt(11)
	v_fma_f32 v63, -v14, v62, v58
	v_mul_f32_e32 v254, v8, v63
	v_pk_fma_f32 v[30:31], v[66:67], v[254:255], v[30:31] op_sel_hi:[1,0,1]
	v_pk_fma_f32 v[44:45], v[68:69], v[254:255], v[44:45] op_sel_hi:[1,0,1]
	v_pk_fma_f32 v[38:39], v[70:71], v[254:255], v[38:39] op_sel_hi:[1,0,1]
	v_pk_fma_f32 v[36:37], v[72:73], v[254:255], v[36:37] op_sel_hi:[1,0,1]
	v_pk_fma_f32 v[34:35], v[74:75], v[254:255], v[34:35] op_sel_hi:[1,0,1]
	v_pk_fma_f32 v[32:33], v[76:77], v[254:255], v[32:33] op_sel_hi:[1,0,1]
	v_pk_fma_f32 v[40:41], v[78:79], v[254:255], v[40:41] op_sel_hi:[1,0,1]
	v_pk_fma_f32 v[42:43], v[80:81], v[254:255], v[42:43] op_sel_hi:[1,0,1]
	ds_read_b128 v[66:69], v65 offset:1024
	ds_read_b128 v[70:73], v65 offset:1040
	ds_read_b128 v[74:77], v65 offset:1056
	ds_read_b128 v[78:81], v65 offset:1072
	s_waitcnt lgkmcnt(11)
	v_pk_mul_f32 v[62:63], v[30:31], v[82:83]
	s_waitcnt lgkmcnt(7)
	v_pk_mul_f32 v[46:47], v[30:31], v[236:237]
	v_pk_mul_f32 v[98:99], v[44:45], v[84:85]
	v_pk_mul_f32 v[252:253], v[44:45], v[238:239]
	v_pk_fma_f32 v[62:63], v[38:39], v[86:87], v[62:63]
	s_waitcnt lgkmcnt(6)
	v_pk_fma_f32 v[46:47], v[38:39], v[240:241], v[46:47]
	v_pk_fma_f32 v[98:99], v[36:37], v[88:89], v[98:99]
	v_pk_fma_f32 v[252:253], v[36:37], v[242:243], v[252:253]
	v_pk_fma_f32 v[62:63], v[34:35], v[90:91], v[62:63]
	s_waitcnt lgkmcnt(5)
	v_pk_fma_f32 v[46:47], v[34:35], v[244:245], v[46:47]
	v_pk_fma_f32 v[98:99], v[32:33], v[92:93], v[98:99]
	v_pk_fma_f32 v[252:253], v[32:33], v[246:247], v[252:253]
	v_pk_fma_f32 v[62:63], v[40:41], v[94:95], v[62:63]
	s_waitcnt lgkmcnt(4)
	v_pk_fma_f32 v[46:47], v[40:41], v[248:249], v[46:47]
	v_pk_fma_f32 v[98:99], v[42:43], v[96:97], v[98:99]
	v_pk_fma_f32 v[252:253], v[42:43], v[250:251], v[252:253]
	v_pk_add_f32 v[62:63], v[62:63], v[98:99]
	v_pk_add_f32 v[46:47], v[46:47], v[252:253]
	ds_read_b128 v[236:239], v65 offset:8704
	ds_read_b128 v[240:243], v65 offset:8720
	ds_read_b128 v[244:247], v65 offset:8736
	ds_read_b128 v[248:251], v65 offset:8752
	v_add_f32_e32 v62, v62, v63
	v_add_f32_e32 v46, v46, v47
	v_pk_mul_f32 v[30:31], v[30:31], v[14:15] op_sel:[0,1]
	v_pk_mul_f32 v[44:45], v[44:45], v[14:15] op_sel:[0,1]
	v_add_f32_dpp v62, v62, v62 quad_perm:[1,0,3,2] row_mask:0xf bank_mask:0xf bound_ctrl:1
	v_add_f32_dpp v46, v46, v46 quad_perm:[1,0,3,2] row_mask:0xf bank_mask:0xf bound_ctrl:1
	v_pk_mul_f32 v[38:39], v[38:39], v[14:15] op_sel:[0,1]
	v_pk_mul_f32 v[36:37], v[36:37], v[14:15] op_sel:[0,1]
	v_add_f32_dpp v62, v62, v62 quad_perm:[2,3,0,1] row_mask:0xf bank_mask:0xf bound_ctrl:1
	v_add_f32_dpp v46, v46, v46 quad_perm:[2,3,0,1] row_mask:0xf bank_mask:0xf bound_ctrl:1
	v_pk_mul_f32 v[34:35], v[34:35], v[14:15] op_sel:[0,1]
	v_pk_mul_f32 v[32:33], v[32:33], v[14:15] op_sel:[0,1]
	v_add_f32_dpp v62, v62, v62 row_half_mirror row_mask:0xf bank_mask:0xf bound_ctrl:1
	v_add_f32_dpp v46, v46, v46 row_half_mirror row_mask:0xf bank_mask:0xf bound_ctrl:1
	v_pk_mul_f32 v[40:41], v[40:41], v[14:15] op_sel:[0,1]
	v_pk_mul_f32 v[42:43], v[42:43], v[14:15] op_sel:[0,1]
	v_fma_f32 v63, -v15, v62, v59
	v_mul_f32_e32 v254, v9, v63
	global_store_dword v[28:29], v46, off offset:-4096
	v_pk_fma_f32 v[30:31], v[82:83], v[254:255], v[30:31] op_sel_hi:[1,0,1]
	v_pk_fma_f32 v[44:45], v[84:85], v[254:255], v[44:45] op_sel_hi:[1,0,1]
	v_pk_fma_f32 v[38:39], v[86:87], v[254:255], v[38:39] op_sel_hi:[1,0,1]
	v_pk_fma_f32 v[36:37], v[88:89], v[254:255], v[36:37] op_sel_hi:[1,0,1]
	v_pk_fma_f32 v[34:35], v[90:91], v[254:255], v[34:35] op_sel_hi:[1,0,1]
	v_pk_fma_f32 v[32:33], v[92:93], v[254:255], v[32:33] op_sel_hi:[1,0,1]
	v_pk_fma_f32 v[40:41], v[94:95], v[254:255], v[40:41] op_sel_hi:[1,0,1]
	v_pk_fma_f32 v[42:43], v[96:97], v[254:255], v[42:43] op_sel_hi:[1,0,1]
	ds_read_b128 v[82:85], v65 offset:1536
	ds_read_b128 v[86:89], v65 offset:1552
	ds_read_b128 v[90:93], v65 offset:1568
	ds_read_b128 v[94:97], v65 offset:1584
	s_waitcnt lgkmcnt(11)
; __device__ __forceinline__ void delta_scan_task(KP p, int l, bool samp, int b, int h, int cgp, float* sm) {
;     ...
;         for (int s0 = 0; s0 < nst; s0 += 4) {
; #pragma unroll
;             for (int s4 = 0; s4 < 4; ++s4) {
;                 const int s = s0 + s4;
;                 f32x2 k2[8], q2[8];
; #pragma unroll
;                 for (int hh = 0; hh < 4; ++hh) {
;                     const float4 a = *(const float4*)(bufp + s * 128 + ks * 16 + hh * 4);
;                     const float4 c = *(const float4*)(bufp + 2048 + s * 128 + ks * 16 + hh * 4);
;                     k2[2 * hh] = (f32x2){a.x, a.y}; k2[2 * hh + 1] = (f32x2){a.z, a.w};
;                     q2[2 * hh] = (f32x2){c.x, c.y}; q2[2 * hh + 1] = (f32x2){c.z, c.w};
;                 }
;                 const float vv = bufp[4096 + s * 32 + wid * 8 + cc];
;                 const float beta = bufp[4608 + s], alpha = bufp[4624 + s];
;                 f32x2 d0 = S[0] * k2[0], d1v = S[1] * k2[1], d2 = S[2] * k2[2], d3 = S[3] * k2[3];
;                 d0 = S[4] * k2[4] + d0; d1v = S[5] * k2[5] + d1v; d2 = S[6] * k2[6] + d2; d3 = S[7] * k2[7] + d3;
;                 d0 = (d0 + d1v) + (d2 + d3);
;                 const f32x2 al2 = (f32x2){alpha, alpha};
;                 f32x2 sa[8];
; #pragma unroll
;                 for (int j = 0; j < 8; ++j) sa[j] = S[j] * al2;
;                 const float dk = red8(d0.x + d0.y);
;                 const float vn = beta * (vv - alpha * dk);
;                 const f32x2 vn2 = (f32x2){vn, vn};
; #pragma unroll
;                 for (int j = 0; j < 8; ++j) S[j] = k2[j] * vn2 + sa[j];
;                 f32x2 o0 = S[0] * q2[0], o1 = S[1] * q2[1], o2 = S[2] * q2[2], o3 = S[3] * q2[3];
;                 o0 = S[4] * q2[4] + o0; o1 = S[5] * q2[5] + o1; o2 = S[6] * q2[6] + o2; o3 = S[7] * q2[7] + o3;
;                 o0 = (o0 + o1) + (o2 + o3);
;                 const float o = red8(o0.x + o0.y);
;                 oraw[(size_t)(row0 + tile * 16 + s) * 512 + h * 128 + e] = o;
;             }
	v_pk_mul_f32 v[62:63], v[30:31], v[66:67]
	s_waitcnt lgkmcnt(7)
	v_pk_mul_f32 v[46:47], v[30:31], v[236:237]
	v_pk_mul_f32 v[98:99], v[44:45], v[68:69]
	v_pk_mul_f32 v[252:253], v[44:45], v[238:239]
	v_pk_fma_f32 v[62:63], v[38:39], v[70:71], v[62:63]
	s_waitcnt lgkmcnt(6)
	v_pk_fma_f32 v[46:47], v[38:39], v[240:241], v[46:47]
	v_pk_fma_f32 v[98:99], v[36:37], v[72:73], v[98:99]
	v_pk_fma_f32 v[252:253], v[36:37], v[242:243], v[252:253]
	v_pk_fma_f32 v[62:63], v[34:35], v[74:75], v[62:63]
	s_waitcnt lgkmcnt(5)
	v_pk_fma_f32 v[46:47], v[34:35], v[244:245], v[46:47]
	v_pk_fma_f32 v[98:99], v[32:33], v[76:77], v[98:99]
	v_pk_fma_f32 v[252:253], v[32:33], v[246:247], v[252:253]
	v_pk_fma_f32 v[62:63], v[40:41], v[78:79], v[62:63]
	s_waitcnt lgkmcnt(4)
	v_pk_fma_f32 v[46:47], v[40:41], v[248:249], v[46:47]
	v_pk_fma_f32 v[98:99], v[42:43], v[80:81], v[98:99]
	v_pk_fma_f32 v[252:253], v[42:43], v[250:251], v[252:253]
	v_pk_add_f32 v[62:63], v[62:63], v[98:99]
	v_pk_add_f32 v[46:47], v[46:47], v[252:253]
	ds_read_b128 v[236:239], v65 offset:9216
	ds_read_b128 v[240:243], v65 offset:9232
	ds_read_b128 v[244:247], v65 offset:9248
	ds_read_b128 v[248:251], v65 offset:9264
	v_add_f32_e32 v62, v62, v63
	v_add_f32_e32 v46, v46, v47
	v_pk_mul_f32 v[30:31], v[30:31], v[16:17] op_sel_hi:[1,0]
	v_pk_mul_f32 v[44:45], v[44:45], v[16:17] op_sel_hi:[1,0]
	v_add_f32_dpp v62, v62, v62 quad_perm:[1,0,3,2] row_mask:0xf bank_mask:0xf bound_ctrl:1
	v_add_f32_dpp v46, v46, v46 quad_perm:[1,0,3,2] row_mask:0xf bank_mask:0xf bound_ctrl:1
	v_pk_mul_f32 v[38:39], v[38:39], v[16:17] op_sel_hi:[1,0]
	v_pk_mul_f32 v[36:37], v[36:37], v[16:17] op_sel_hi:[1,0]
	v_add_f32_dpp v62, v62, v62 quad_perm:[2,3,0,1] row_mask:0xf bank_mask:0xf bound_ctrl:1
	v_add_f32_dpp v46, v46, v46 quad_perm:[2,3,0,1] row_mask:0xf bank_mask:0xf bound_ctrl:1
	v_pk_mul_f32 v[34:35], v[34:35], v[16:17] op_sel_hi:[1,0]
	v_pk_mul_f32 v[32:33], v[32:33], v[16:17] op_sel_hi:[1,0]
	v_add_f32_dpp v62, v62, v62 row_half_mirror row_mask:0xf bank_mask:0xf bound_ctrl:1
	v_add_f32_dpp v46, v46, v46 row_half_mirror row_mask:0xf bank_mask:0xf bound_ctrl:1
	v_pk_mul_f32 v[40:41], v[40:41], v[16:17] op_sel_hi:[1,0]
	v_pk_mul_f32 v[42:43], v[42:43], v[16:17] op_sel_hi:[1,0]
	v_fma_f32 v63, -v16, v62, v60
	v_mul_f32_e32 v254, v10, v63
	global_store_dword v[28:29], v46, off offset:-2048
	v_pk_fma_f32 v[30:31], v[66:67], v[254:255], v[30:31] op_sel_hi:[1,0,1]
	v_pk_fma_f32 v[44:45], v[68:69], v[254:255], v[44:45] op_sel_hi:[1,0,1]
	v_pk_fma_f32 v[38:39], v[70:71], v[254:255], v[38:39] op_sel_hi:[1,0,1]
	v_pk_fma_f32 v[36:37], v[72:73], v[254:255], v[36:37] op_sel_hi:[1,0,1]
	v_pk_fma_f32 v[34:35], v[74:75], v[254:255], v[34:35] op_sel_hi:[1,0,1]
	v_pk_fma_f32 v[32:33], v[76:77], v[254:255], v[32:33] op_sel_hi:[1,0,1]
	v_pk_fma_f32 v[40:41], v[78:79], v[254:255], v[40:41] op_sel_hi:[1,0,1]
	v_pk_fma_f32 v[42:43], v[80:81], v[254:255], v[42:43] op_sel_hi:[1,0,1]
	ds_read_b128 v[66:69], v65 offset:2048
	ds_read_b128 v[70:73], v65 offset:2064
	ds_read_b128 v[74:77], v65 offset:2080
	ds_read_b128 v[78:81], v65 offset:2096
	s_waitcnt lgkmcnt(11)
	v_pk_mul_f32 v[62:63], v[30:31], v[82:83]
	s_waitcnt lgkmcnt(7)
	v_pk_mul_f32 v[46:47], v[30:31], v[236:237]
	v_pk_mul_f32 v[98:99], v[44:45], v[84:85]
	v_pk_mul_f32 v[252:253], v[44:45], v[238:239]
	v_pk_fma_f32 v[62:63], v[38:39], v[86:87], v[62:63]
	s_waitcnt lgkmcnt(6)
	v_pk_fma_f32 v[46:47], v[38:39], v[240:241], v[46:47]
	v_pk_fma_f32 v[98:99], v[36:37], v[88:89], v[98:99]
	v_pk_fma_f32 v[252:253], v[36:37], v[242:243], v[252:253]
	v_pk_fma_f32 v[62:63], v[34:35], v[90:91], v[62:63]
	s_waitcnt lgkmcnt(5)
	v_pk_fma_f32 v[46:47], v[34:35], v[244:245], v[46:47]
	v_pk_fma_f32 v[98:99], v[32:33], v[92:93], v[98:99]
	v_pk_fma_f32 v[252:253], v[32:33], v[246:247], v[252:253]
	v_pk_fma_f32 v[62:63], v[40:41], v[94:95], v[62:63]
	s_waitcnt lgkmcnt(4)
	v_pk_fma_f32 v[46:47], v[40:41], v[248:249], v[46:47]
	v_pk_fma_f32 v[98:99], v[42:43], v[96:97], v[98:99]
	v_pk_fma_f32 v[252:253], v[42:43], v[250:251], v[252:253]
	v_pk_add_f32 v[62:63], v[62:63], v[98:99]
	v_pk_add_f32 v[46:47], v[46:47], v[252:253]
	ds_read_b128 v[236:239], v65 offset:9728
	ds_read_b128 v[240:243], v65 offset:9744
	ds_read_b128 v[244:247], v65 offset:9760
	ds_read_b128 v[248:251], v65 offset:9776
	v_add_f32_e32 v62, v62, v63
	v_add_f32_e32 v46, v46, v47
	v_pk_mul_f32 v[30:31], v[30:31], v[16:17] op_sel:[0,1]
	v_pk_mul_f32 v[44:45], v[44:45], v[16:17] op_sel:[0,1]
	v_add_f32_dpp v62, v62, v62 quad_perm:[1,0,3,2] row_mask:0xf bank_mask:0xf bound_ctrl:1
	v_add_f32_dpp v46, v46, v46 quad_perm:[1,0,3,2] row_mask:0xf bank_mask:0xf bound_ctrl:1
	v_pk_mul_f32 v[38:39], v[38:39], v[16:17] op_sel:[0,1]
	v_pk_mul_f32 v[36:37], v[36:37], v[16:17] op_sel:[0,1]
	v_add_f32_dpp v62, v62, v62 quad_perm:[2,3,0,1] row_mask:0xf bank_mask:0xf bound_ctrl:1
	v_add_f32_dpp v46, v46, v46 quad_perm:[2,3,0,1] row_mask:0xf bank_mask:0xf bound_ctrl:1
	v_pk_mul_f32 v[34:35], v[34:35], v[16:17] op_sel:[0,1]
	v_pk_mul_f32 v[32:33], v[32:33], v[16:17] op_sel:[0,1]
	v_add_f32_dpp v62, v62, v62 row_half_mirror row_mask:0xf bank_mask:0xf bound_ctrl:1
	v_add_f32_dpp v46, v46, v46 row_half_mirror row_mask:0xf bank_mask:0xf bound_ctrl:1
	v_pk_mul_f32 v[40:41], v[40:41], v[16:17] op_sel:[0,1]
	v_pk_mul_f32 v[42:43], v[42:43], v[16:17] op_sel:[0,1]
	v_fma_f32 v63, -v17, v62, v61
	v_mul_f32_e32 v254, v11, v63
	global_store_dword v[28:29], v46, off
	v_pk_fma_f32 v[30:31], v[82:83], v[254:255], v[30:31] op_sel_hi:[1,0,1]
	v_pk_fma_f32 v[44:45], v[84:85], v[254:255], v[44:45] op_sel_hi:[1,0,1]
	v_pk_fma_f32 v[38:39], v[86:87], v[254:255], v[38:39] op_sel_hi:[1,0,1]
	v_pk_fma_f32 v[36:37], v[88:89], v[254:255], v[36:37] op_sel_hi:[1,0,1]
	v_pk_fma_f32 v[34:35], v[90:91], v[254:255], v[34:35] op_sel_hi:[1,0,1]
	v_pk_fma_f32 v[32:33], v[92:93], v[254:255], v[32:33] op_sel_hi:[1,0,1]
	v_pk_fma_f32 v[40:41], v[94:95], v[254:255], v[40:41] op_sel_hi:[1,0,1]
	v_pk_fma_f32 v[42:43], v[96:97], v[254:255], v[42:43] op_sel_hi:[1,0,1]
	ds_read_b128 v[14:17], v234 offset:80
	ds_read_b128 v[8:11], v234 offset:16
	ds_read_b32 v58, v100 offset:512
	ds_read_b32 v59, v100 offset:640
	ds_read_b32 v60, v100 offset:768
	ds_read_b32 v61, v100 offset:896
	ds_read_b128 v[82:85], v65 offset:2560
	ds_read_b128 v[86:89], v65 offset:2576
	ds_read_b128 v[90:93], v65 offset:2592
	ds_read_b128 v[94:97], v65 offset:2608
	s_waitcnt lgkmcnt(15)
; __device__ __forceinline__ void delta_scan_task(KP p, int l, bool samp, int b, int h, int cgp, float* sm) {
;     ...
;         for (int s0 = 0; s0 < nst; s0 += 4) {
; #pragma unroll
;             for (int s4 = 0; s4 < 4; ++s4) {
;                 const int s = s0 + s4;
;                 f32x2 k2[8], q2[8];
; #pragma unroll
;                 for (int hh = 0; hh < 4; ++hh) {
;                     const float4 a = *(const float4*)(bufp + s * 128 + ks * 16 + hh * 4);
;                     const float4 c = *(const float4*)(bufp + 2048 + s * 128 + ks * 16 + hh * 4);
;                     k2[2 * hh] = (f32x2){a.x, a.y}; k2[2 * hh + 1] = (f32x2){a.z, a.w};
;                     q2[2 * hh] = (f32x2){c.x, c.y}; q2[2 * hh + 1] = (f32x2){c.z, c.w};
;                 }
;                 const float vv = bufp[4096 + s * 32 + wid * 8 + cc];
;                 const float beta = bufp[4608 + s], alpha = bufp[4624 + s];
;                 f32x2 d0 = S[0] * k2[0], d1v = S[1] * k2[1], d2 = S[2] * k2[2], d3 = S[3] * k2[3];
;                 d0 = S[4] * k2[4] + d0; d1v = S[5] * k2[5] + d1v; d2 = S[6] * k2[6] + d2; d3 = S[7] * k2[7] + d3;
;                 d0 = (d0 + d1v) + (d2 + d3);
;                 const f32x2 al2 = (f32x2){alpha, alpha};
;                 f32x2 sa[8];
; #pragma unroll
;                 for (int j = 0; j < 8; ++j) sa[j] = S[j] * al2;
;                 const float dk = red8(d0.x + d0.y);
;                 const float vn = beta * (vv - alpha * dk);
;                 const f32x2 vn2 = (f32x2){vn, vn};
; #pragma unroll
;                 for (int j = 0; j < 8; ++j) S[j] = k2[j] * vn2 + sa[j];
;                 f32x2 o0 = S[0] * q2[0], o1 = S[1] * q2[1], o2 = S[2] * q2[2], o3 = S[3] * q2[3];
;                 o0 = S[4] * q2[4] + o0; o1 = S[5] * q2[5] + o1; o2 = S[6] * q2[6] + o2; o3 = S[7] * q2[7] + o3;
;                 o0 = (o0 + o1) + (o2 + o3);
;                 const float o = red8(o0.x + o0.y);
;                 oraw[(size_t)(row0 + tile * 16 + s) * 512 + h * 128 + e] = o;
;             }
	v_pk_mul_f32 v[62:63], v[30:31], v[66:67]
	s_waitcnt lgkmcnt(13)
	v_pk_mul_f32 v[46:47], v[30:31], v[236:237]
	v_pk_mul_f32 v[98:99], v[44:45], v[68:69]
	v_pk_mul_f32 v[252:253], v[44:45], v[238:239]
	v_pk_fma_f32 v[62:63], v[38:39], v[70:71], v[62:63]
	s_waitcnt lgkmcnt(12)
	v_pk_fma_f32 v[46:47], v[38:39], v[240:241], v[46:47]
	v_pk_fma_f32 v[98:99], v[36:37], v[72:73], v[98:99]
	v_pk_fma_f32 v[252:253], v[36:37], v[242:243], v[252:253]
	v_pk_fma_f32 v[62:63], v[34:35], v[74:75], v[62:63]
	s_waitcnt lgkmcnt(11)
	v_pk_fma_f32 v[46:47], v[34:35], v[244:245], v[46:47]
	v_pk_fma_f32 v[98:99], v[32:33], v[76:77], v[98:99]
	v_pk_fma_f32 v[252:253], v[32:33], v[246:247], v[252:253]
	v_pk_fma_f32 v[62:63], v[40:41], v[78:79], v[62:63]
	s_waitcnt lgkmcnt(10)
	v_pk_fma_f32 v[46:47], v[40:41], v[248:249], v[46:47]
	v_pk_fma_f32 v[98:99], v[42:43], v[80:81], v[98:99]
	v_pk_fma_f32 v[252:253], v[42:43], v[250:251], v[252:253]
	v_pk_add_f32 v[62:63], v[62:63], v[98:99]
	v_pk_add_f32 v[46:47], v[46:47], v[252:253]
	ds_read_b128 v[236:239], v65 offset:10240
	ds_read_b128 v[240:243], v65 offset:10256
	ds_read_b128 v[244:247], v65 offset:10272
	ds_read_b128 v[248:251], v65 offset:10288
	v_add_f32_e32 v62, v62, v63
	v_add_f32_e32 v46, v46, v47
	s_waitcnt lgkmcnt(13)
	v_pk_mul_f32 v[30:31], v[30:31], v[14:15] op_sel_hi:[1,0]
	v_pk_mul_f32 v[44:45], v[44:45], v[14:15] op_sel_hi:[1,0]
	v_add_f32_dpp v62, v62, v62 quad_perm:[1,0,3,2] row_mask:0xf bank_mask:0xf bound_ctrl:1
	v_add_f32_dpp v46, v46, v46 quad_perm:[1,0,3,2] row_mask:0xf bank_mask:0xf bound_ctrl:1
	v_pk_mul_f32 v[38:39], v[38:39], v[14:15] op_sel_hi:[1,0]
	v_pk_mul_f32 v[36:37], v[36:37], v[14:15] op_sel_hi:[1,0]
	v_add_f32_dpp v62, v62, v62 quad_perm:[2,3,0,1] row_mask:0xf bank_mask:0xf bound_ctrl:1
	v_add_f32_dpp v46, v46, v46 quad_perm:[2,3,0,1] row_mask:0xf bank_mask:0xf bound_ctrl:1
	v_pk_mul_f32 v[34:35], v[34:35], v[14:15] op_sel_hi:[1,0]
	v_pk_mul_f32 v[32:33], v[32:33], v[14:15] op_sel_hi:[1,0]
	v_add_f32_dpp v62, v62, v62 row_half_mirror row_mask:0xf bank_mask:0xf bound_ctrl:1
	v_add_f32_dpp v46, v46, v46 row_half_mirror row_mask:0xf bank_mask:0xf bound_ctrl:1
	v_pk_mul_f32 v[40:41], v[40:41], v[14:15] op_sel_hi:[1,0]
	v_pk_mul_f32 v[42:43], v[42:43], v[14:15] op_sel_hi:[1,0]
	s_waitcnt lgkmcnt(11)
	v_fma_f32 v63, -v14, v62, v58
	v_mul_f32_e32 v254, v8, v63
	global_store_dword v[28:29], v46, off offset:2048
	v_lshl_add_u64 v[28:29], v[28:29], 0, s[20:21]
	v_pk_fma_f32 v[30:31], v[66:67], v[254:255], v[30:31] op_sel_hi:[1,0,1]
	v_pk_fma_f32 v[44:45], v[68:69], v[254:255], v[44:45] op_sel_hi:[1,0,1]
	v_pk_fma_f32 v[38:39], v[70:71], v[254:255], v[38:39] op_sel_hi:[1,0,1]
	v_pk_fma_f32 v[36:37], v[72:73], v[254:255], v[36:37] op_sel_hi:[1,0,1]
	v_pk_fma_f32 v[34:35], v[74:75], v[254:255], v[34:35] op_sel_hi:[1,0,1]
	v_pk_fma_f32 v[32:33], v[76:77], v[254:255], v[32:33] op_sel_hi:[1,0,1]
	v_pk_fma_f32 v[40:41], v[78:79], v[254:255], v[40:41] op_sel_hi:[1,0,1]
	v_pk_fma_f32 v[42:43], v[80:81], v[254:255], v[42:43] op_sel_hi:[1,0,1]
	ds_read_b128 v[66:69], v65 offset:3072
	ds_read_b128 v[70:73], v65 offset:3088
	ds_read_b128 v[74:77], v65 offset:3104
	ds_read_b128 v[78:81], v65 offset:3120
	s_waitcnt lgkmcnt(11)
	v_pk_mul_f32 v[62:63], v[30:31], v[82:83]
	s_waitcnt lgkmcnt(7)
	v_pk_mul_f32 v[46:47], v[30:31], v[236:237]
	v_pk_mul_f32 v[98:99], v[44:45], v[84:85]
	v_pk_mul_f32 v[252:253], v[44:45], v[238:239]
	v_pk_fma_f32 v[62:63], v[38:39], v[86:87], v[62:63]
	s_waitcnt lgkmcnt(6)
	v_pk_fma_f32 v[46:47], v[38:39], v[240:241], v[46:47]
	v_pk_fma_f32 v[98:99], v[36:37], v[88:89], v[98:99]
	v_pk_fma_f32 v[252:253], v[36:37], v[242:243], v[252:253]
	v_pk_fma_f32 v[62:63], v[34:35], v[90:91], v[62:63]
	s_waitcnt lgkmcnt(5)
	v_pk_fma_f32 v[46:47], v[34:35], v[244:245], v[46:47]
	v_pk_fma_f32 v[98:99], v[32:33], v[92:93], v[98:99]
	v_pk_fma_f32 v[252:253], v[32:33], v[246:247], v[252:253]
	v_pk_fma_f32 v[62:63], v[40:41], v[94:95], v[62:63]
	s_waitcnt lgkmcnt(4)
	v_pk_fma_f32 v[46:47], v[40:41], v[248:249], v[46:47]
	v_pk_fma_f32 v[98:99], v[42:43], v[96:97], v[98:99]
	v_pk_fma_f32 v[252:253], v[42:43], v[250:251], v[252:253]
	v_pk_add_f32 v[62:63], v[62:63], v[98:99]
	v_pk_add_f32 v[46:47], v[46:47], v[252:253]
	ds_read_b128 v[236:239], v65 offset:10752
	ds_read_b128 v[240:243], v65 offset:10768
	ds_read_b128 v[244:247], v65 offset:10784
	ds_read_b128 v[248:251], v65 offset:10800
	v_add_f32_e32 v62, v62, v63
	v_add_f32_e32 v46, v46, v47
	v_pk_mul_f32 v[30:31], v[30:31], v[14:15] op_sel:[0,1]
	v_pk_mul_f32 v[44:45], v[44:45], v[14:15] op_sel:[0,1]
	v_add_f32_dpp v62, v62, v62 quad_perm:[1,0,3,2] row_mask:0xf bank_mask:0xf bound_ctrl:1
	v_add_f32_dpp v46, v46, v46 quad_perm:[1,0,3,2] row_mask:0xf bank_mask:0xf bound_ctrl:1
	v_pk_mul_f32 v[38:39], v[38:39], v[14:15] op_sel:[0,1]
	v_pk_mul_f32 v[36:37], v[36:37], v[14:15] op_sel:[0,1]
	v_add_f32_dpp v62, v62, v62 quad_perm:[2,3,0,1] row_mask:0xf bank_mask:0xf bound_ctrl:1
	v_add_f32_dpp v46, v46, v46 quad_perm:[2,3,0,1] row_mask:0xf bank_mask:0xf bound_ctrl:1
	v_pk_mul_f32 v[34:35], v[34:35], v[14:15] op_sel:[0,1]
	v_pk_mul_f32 v[32:33], v[32:33], v[14:15] op_sel:[0,1]
	v_add_f32_dpp v62, v62, v62 row_half_mirror row_mask:0xf bank_mask:0xf bound_ctrl:1
	v_add_f32_dpp v46, v46, v46 row_half_mirror row_mask:0xf bank_mask:0xf bound_ctrl:1
	v_pk_mul_f32 v[40:41], v[40:41], v[14:15] op_sel:[0,1]
	v_pk_mul_f32 v[42:43], v[42:43], v[14:15] op_sel:[0,1]
	v_fma_f32 v63, -v15, v62, v59
	v_mul_f32_e32 v254, v9, v63
	global_store_dword v[28:29], v46, off offset:-4096
	v_pk_fma_f32 v[30:31], v[82:83], v[254:255], v[30:31] op_sel_hi:[1,0,1]
	v_pk_fma_f32 v[44:45], v[84:85], v[254:255], v[44:45] op_sel_hi:[1,0,1]
	v_pk_fma_f32 v[38:39], v[86:87], v[254:255], v[38:39] op_sel_hi:[1,0,1]
	v_pk_fma_f32 v[36:37], v[88:89], v[254:255], v[36:37] op_sel_hi:[1,0,1]
	v_pk_fma_f32 v[34:35], v[90:91], v[254:255], v[34:35] op_sel_hi:[1,0,1]
	v_pk_fma_f32 v[32:33], v[92:93], v[254:255], v[32:33] op_sel_hi:[1,0,1]
	v_pk_fma_f32 v[40:41], v[94:95], v[254:255], v[40:41] op_sel_hi:[1,0,1]
	v_pk_fma_f32 v[42:43], v[96:97], v[254:255], v[42:43] op_sel_hi:[1,0,1]
	ds_read_b128 v[82:85], v65 offset:3584
	ds_read_b128 v[86:89], v65 offset:3600
	ds_read_b128 v[90:93], v65 offset:3616
	ds_read_b128 v[94:97], v65 offset:3632
	s_waitcnt lgkmcnt(11)
; __device__ __forceinline__ void delta_scan_task(KP p, int l, bool samp, int b, int h, int cgp, float* sm) {
;     ...
;         for (int s0 = 0; s0 < nst; s0 += 4) {
; #pragma unroll
;             for (int s4 = 0; s4 < 4; ++s4) {
;                 const int s = s0 + s4;
;                 f32x2 k2[8], q2[8];
; #pragma unroll
;                 for (int hh = 0; hh < 4; ++hh) {
;                     const float4 a = *(const float4*)(bufp + s * 128 + ks * 16 + hh * 4);
;                     const float4 c = *(const float4*)(bufp + 2048 + s * 128 + ks * 16 + hh * 4);
;                     k2[2 * hh] = (f32x2){a.x, a.y}; k2[2 * hh + 1] = (f32x2){a.z, a.w};
;                     q2[2 * hh] = (f32x2){c.x, c.y}; q2[2 * hh + 1] = (f32x2){c.z, c.w};
;                 }
;                 const float vv = bufp[4096 + s * 32 + wid * 8 + cc];
;                 const float beta = bufp[4608 + s], alpha = bufp[4624 + s];
;                 f32x2 d0 = S[0] * k2[0], d1v = S[1] * k2[1], d2 = S[2] * k2[2], d3 = S[3] * k2[3];
;                 d0 = S[4] * k2[4] + d0; d1v = S[5] * k2[5] + d1v; d2 = S[6] * k2[6] + d2; d3 = S[7] * k2[7] + d3;
;                 d0 = (d0 + d1v) + (d2 + d3);
;                 const f32x2 al2 = (f32x2){alpha, alpha};
;                 f32x2 sa[8];
; #pragma unroll
;                 for (int j = 0; j < 8; ++j) sa[j] = S[j] * al2;
;                 const float dk = red8(d0.x + d0.y);
;                 const float vn = beta * (vv - alpha * dk);
;                 const f32x2 vn2 = (f32x2){vn, vn};
; #pragma unroll
;                 for (int j = 0; j < 8; ++j) S[j] = k2[j] * vn2 + sa[j];
;                 f32x2 o0 = S[0] * q2[0], o1 = S[1] * q2[1], o2 = S[2] * q2[2], o3 = S[3] * q2[3];
;                 o0 = S[4] * q2[4] + o0; o1 = S[5] * q2[5] + o1; o2 = S[6] * q2[6] + o2; o3 = S[7] * q2[7] + o3;
;                 o0 = (o0 + o1) + (o2 + o3);
;                 const float o = red8(o0.x + o0.y);
;                 oraw[(size_t)(row0 + tile * 16 + s) * 512 + h * 128 + e] = o;
;             }
	v_pk_mul_f32 v[62:63], v[30:31], v[66:67]
	s_waitcnt lgkmcnt(7)
	v_pk_mul_f32 v[46:47], v[30:31], v[236:237]
	v_pk_mul_f32 v[98:99], v[44:45], v[68:69]
	v_pk_mul_f32 v[252:253], v[44:45], v[238:239]
	v_pk_fma_f32 v[62:63], v[38:39], v[70:71], v[62:63]
	s_waitcnt lgkmcnt(6)
	v_pk_fma_f32 v[46:47], v[38:39], v[240:241], v[46:47]
	v_pk_fma_f32 v[98:99], v[36:37], v[72:73], v[98:99]
	v_pk_fma_f32 v[252:253], v[36:37], v[242:243], v[252:253]
	v_pk_fma_f32 v[62:63], v[34:35], v[74:75], v[62:63]
	s_waitcnt lgkmcnt(5)
	v_pk_fma_f32 v[46:47], v[34:35], v[244:245], v[46:47]
	v_pk_fma_f32 v[98:99], v[32:33], v[76:77], v[98:99]
	v_pk_fma_f32 v[252:253], v[32:33], v[246:247], v[252:253]
	v_pk_fma_f32 v[62:63], v[40:41], v[78:79], v[62:63]
	s_waitcnt lgkmcnt(4)
	v_pk_fma_f32 v[46:47], v[40:41], v[248:249], v[46:47]
	v_pk_fma_f32 v[98:99], v[42:43], v[80:81], v[98:99]
	v_pk_fma_f32 v[252:253], v[42:43], v[250:251], v[252:253]
	v_pk_add_f32 v[62:63], v[62:63], v[98:99]
	v_pk_add_f32 v[46:47], v[46:47], v[252:253]
	ds_read_b128 v[236:239], v65 offset:11264
	ds_read_b128 v[240:243], v65 offset:11280
	ds_read_b128 v[244:247], v65 offset:11296
	ds_read_b128 v[248:251], v65 offset:11312
	v_add_f32_e32 v62, v62, v63
	v_add_f32_e32 v46, v46, v47
	v_pk_mul_f32 v[30:31], v[30:31], v[16:17] op_sel_hi:[1,0]
	v_pk_mul_f32 v[44:45], v[44:45], v[16:17] op_sel_hi:[1,0]
	v_add_f32_dpp v62, v62, v62 quad_perm:[1,0,3,2] row_mask:0xf bank_mask:0xf bound_ctrl:1
	v_add_f32_dpp v46, v46, v46 quad_perm:[1,0,3,2] row_mask:0xf bank_mask:0xf bound_ctrl:1
	v_pk_mul_f32 v[38:39], v[38:39], v[16:17] op_sel_hi:[1,0]
	v_pk_mul_f32 v[36:37], v[36:37], v[16:17] op_sel_hi:[1,0]
	v_add_f32_dpp v62, v62, v62 quad_perm:[2,3,0,1] row_mask:0xf bank_mask:0xf bound_ctrl:1
	v_add_f32_dpp v46, v46, v46 quad_perm:[2,3,0,1] row_mask:0xf bank_mask:0xf bound_ctrl:1
	v_pk_mul_f32 v[34:35], v[34:35], v[16:17] op_sel_hi:[1,0]
	v_pk_mul_f32 v[32:33], v[32:33], v[16:17] op_sel_hi:[1,0]
	v_add_f32_dpp v62, v62, v62 row_half_mirror row_mask:0xf bank_mask:0xf bound_ctrl:1
	v_add_f32_dpp v46, v46, v46 row_half_mirror row_mask:0xf bank_mask:0xf bound_ctrl:1
	v_pk_mul_f32 v[40:41], v[40:41], v[16:17] op_sel_hi:[1,0]
	v_pk_mul_f32 v[42:43], v[42:43], v[16:17] op_sel_hi:[1,0]
	v_fma_f32 v63, -v16, v62, v60
	v_mul_f32_e32 v254, v10, v63
	global_store_dword v[28:29], v46, off offset:-2048
	v_pk_fma_f32 v[30:31], v[66:67], v[254:255], v[30:31] op_sel_hi:[1,0,1]
	v_pk_fma_f32 v[44:45], v[68:69], v[254:255], v[44:45] op_sel_hi:[1,0,1]
	v_pk_fma_f32 v[38:39], v[70:71], v[254:255], v[38:39] op_sel_hi:[1,0,1]
	v_pk_fma_f32 v[36:37], v[72:73], v[254:255], v[36:37] op_sel_hi:[1,0,1]
	v_pk_fma_f32 v[34:35], v[74:75], v[254:255], v[34:35] op_sel_hi:[1,0,1]
	v_pk_fma_f32 v[32:33], v[76:77], v[254:255], v[32:33] op_sel_hi:[1,0,1]
	v_pk_fma_f32 v[40:41], v[78:79], v[254:255], v[40:41] op_sel_hi:[1,0,1]
	v_pk_fma_f32 v[42:43], v[80:81], v[254:255], v[42:43] op_sel_hi:[1,0,1]
	ds_read_b128 v[66:69], v65 offset:4096
	ds_read_b128 v[70:73], v65 offset:4112
	ds_read_b128 v[74:77], v65 offset:4128
	ds_read_b128 v[78:81], v65 offset:4144
	s_waitcnt lgkmcnt(11)
	v_pk_mul_f32 v[62:63], v[30:31], v[82:83]
	s_waitcnt lgkmcnt(7)
	v_pk_mul_f32 v[46:47], v[30:31], v[236:237]
	v_pk_mul_f32 v[98:99], v[44:45], v[84:85]
	v_pk_mul_f32 v[252:253], v[44:45], v[238:239]
	v_pk_fma_f32 v[62:63], v[38:39], v[86:87], v[62:63]
	s_waitcnt lgkmcnt(6)
	v_pk_fma_f32 v[46:47], v[38:39], v[240:241], v[46:47]
	v_pk_fma_f32 v[98:99], v[36:37], v[88:89], v[98:99]
	v_pk_fma_f32 v[252:253], v[36:37], v[242:243], v[252:253]
	v_pk_fma_f32 v[62:63], v[34:35], v[90:91], v[62:63]
	s_waitcnt lgkmcnt(5)
	v_pk_fma_f32 v[46:47], v[34:35], v[244:245], v[46:47]
	v_pk_fma_f32 v[98:99], v[32:33], v[92:93], v[98:99]
	v_pk_fma_f32 v[252:253], v[32:33], v[246:247], v[252:253]
	v_pk_fma_f32 v[62:63], v[40:41], v[94:95], v[62:63]
	s_waitcnt lgkmcnt(4)
	v_pk_fma_f32 v[46:47], v[40:41], v[248:249], v[46:47]
	v_pk_fma_f32 v[98:99], v[42:43], v[96:97], v[98:99]
	v_pk_fma_f32 v[252:253], v[42:43], v[250:251], v[252:253]
	v_pk_add_f32 v[62:63], v[62:63], v[98:99]
	v_pk_add_f32 v[46:47], v[46:47], v[252:253]
	ds_read_b128 v[236:239], v65 offset:11776
	ds_read_b128 v[240:243], v65 offset:11792
	ds_read_b128 v[244:247], v65 offset:11808
	ds_read_b128 v[248:251], v65 offset:11824
	v_add_f32_e32 v62, v62, v63
	v_add_f32_e32 v46, v46, v47
	v_pk_mul_f32 v[30:31], v[30:31], v[16:17] op_sel:[0,1]
	v_pk_mul_f32 v[44:45], v[44:45], v[16:17] op_sel:[0,1]
	v_add_f32_dpp v62, v62, v62 quad_perm:[1,0,3,2] row_mask:0xf bank_mask:0xf bound_ctrl:1
	v_add_f32_dpp v46, v46, v46 quad_perm:[1,0,3,2] row_mask:0xf bank_mask:0xf bound_ctrl:1
	v_pk_mul_f32 v[38:39], v[38:39], v[16:17] op_sel:[0,1]
	v_pk_mul_f32 v[36:37], v[36:37], v[16:17] op_sel:[0,1]
	v_add_f32_dpp v62, v62, v62 quad_perm:[2,3,0,1] row_mask:0xf bank_mask:0xf bound_ctrl:1
	v_add_f32_dpp v46, v46, v46 quad_perm:[2,3,0,1] row_mask:0xf bank_mask:0xf bound_ctrl:1
	v_pk_mul_f32 v[34:35], v[34:35], v[16:17] op_sel:[0,1]
	v_pk_mul_f32 v[32:33], v[32:33], v[16:17] op_sel:[0,1]
	v_add_f32_dpp v62, v62, v62 row_half_mirror row_mask:0xf bank_mask:0xf bound_ctrl:1
	v_add_f32_dpp v46, v46, v46 row_half_mirror row_mask:0xf bank_mask:0xf bound_ctrl:1
	v_pk_mul_f32 v[40:41], v[40:41], v[16:17] op_sel:[0,1]
	v_pk_mul_f32 v[42:43], v[42:43], v[16:17] op_sel:[0,1]
	v_fma_f32 v63, -v17, v62, v61
	v_mul_f32_e32 v254, v11, v63
	global_store_dword v[28:29], v46, off
	v_pk_fma_f32 v[30:31], v[82:83], v[254:255], v[30:31] op_sel_hi:[1,0,1]
	v_pk_fma_f32 v[44:45], v[84:85], v[254:255], v[44:45] op_sel_hi:[1,0,1]
	v_pk_fma_f32 v[38:39], v[86:87], v[254:255], v[38:39] op_sel_hi:[1,0,1]
	v_pk_fma_f32 v[36:37], v[88:89], v[254:255], v[36:37] op_sel_hi:[1,0,1]
	v_pk_fma_f32 v[34:35], v[90:91], v[254:255], v[34:35] op_sel_hi:[1,0,1]
	v_pk_fma_f32 v[32:33], v[92:93], v[254:255], v[32:33] op_sel_hi:[1,0,1]
	v_pk_fma_f32 v[40:41], v[94:95], v[254:255], v[40:41] op_sel_hi:[1,0,1]
	v_pk_fma_f32 v[42:43], v[96:97], v[254:255], v[42:43] op_sel_hi:[1,0,1]
	ds_read_b128 v[14:17], v234 offset:96
	ds_read_b128 v[8:11], v234 offset:32
	ds_read_b32 v58, v100 offset:1024
	ds_read_b32 v59, v100 offset:1152
	ds_read_b32 v60, v100 offset:1280
	ds_read_b32 v61, v100 offset:1408
	ds_read_b128 v[82:85], v65 offset:4608
	ds_read_b128 v[86:89], v65 offset:4624
	ds_read_b128 v[90:93], v65 offset:4640
	ds_read_b128 v[94:97], v65 offset:4656
	s_waitcnt lgkmcnt(15)
; __device__ __forceinline__ void delta_scan_task(KP p, int l, bool samp, int b, int h, int cgp, float* sm) {
;     ...
;         for (int s0 = 0; s0 < nst; s0 += 4) {
; #pragma unroll
;             for (int s4 = 0; s4 < 4; ++s4) {
;                 const int s = s0 + s4;
;                 f32x2 k2[8], q2[8];
; #pragma unroll
;                 for (int hh = 0; hh < 4; ++hh) {
;                     const float4 a = *(const float4*)(bufp + s * 128 + ks * 16 + hh * 4);
;                     const float4 c = *(const float4*)(bufp + 2048 + s * 128 + ks * 16 + hh * 4);
;                     k2[2 * hh] = (f32x2){a.x, a.y}; k2[2 * hh + 1] = (f32x2){a.z, a.w};
;                     q2[2 * hh] = (f32x2){c.x, c.y}; q2[2 * hh + 1] = (f32x2){c.z, c.w};
;                 }
;                 const float vv = bufp[4096 + s * 32 + wid * 8 + cc];
;                 const float beta = bufp[4608 + s], alpha = bufp[4624 + s];
;                 f32x2 d0 = S[0] * k2[0], d1v = S[1] * k2[1], d2 = S[2] * k2[2], d3 = S[3] * k2[3];
;                 d0 = S[4] * k2[4] + d0; d1v = S[5] * k2[5] + d1v; d2 = S[6] * k2[6] + d2; d3 = S[7] * k2[7] + d3;
;                 d0 = (d0 + d1v) + (d2 + d3);
;                 const f32x2 al2 = (f32x2){alpha, alpha};
;                 f32x2 sa[8];
; #pragma unroll
;                 for (int j = 0; j < 8; ++j) sa[j] = S[j] * al2;
;                 const float dk = red8(d0.x + d0.y);
;                 const float vn = beta * (vv - alpha * dk);
;                 const f32x2 vn2 = (f32x2){vn, vn};
; #pragma unroll
;                 for (int j = 0; j < 8; ++j) S[j] = k2[j] * vn2 + sa[j];
;                 f32x2 o0 = S[0] * q2[0], o1 = S[1] * q2[1], o2 = S[2] * q2[2], o3 = S[3] * q2[3];
;                 o0 = S[4] * q2[4] + o0; o1 = S[5] * q2[5] + o1; o2 = S[6] * q2[6] + o2; o3 = S[7] * q2[7] + o3;
;                 o0 = (o0 + o1) + (o2 + o3);
;                 const float o = red8(o0.x + o0.y);
;                 oraw[(size_t)(row0 + tile * 16 + s) * 512 + h * 128 + e] = o;
;             }
	v_pk_mul_f32 v[62:63], v[30:31], v[66:67]
	s_waitcnt lgkmcnt(13)
	v_pk_mul_f32 v[46:47], v[30:31], v[236:237]
	v_pk_mul_f32 v[98:99], v[44:45], v[68:69]
	v_pk_mul_f32 v[252:253], v[44:45], v[238:239]
	v_pk_fma_f32 v[62:63], v[38:39], v[70:71], v[62:63]
	s_waitcnt lgkmcnt(12)
	v_pk_fma_f32 v[46:47], v[38:39], v[240:241], v[46:47]
	v_pk_fma_f32 v[98:99], v[36:37], v[72:73], v[98:99]
	v_pk_fma_f32 v[252:253], v[36:37], v[242:243], v[252:253]
	v_pk_fma_f32 v[62:63], v[34:35], v[74:75], v[62:63]
	s_waitcnt lgkmcnt(11)
	v_pk_fma_f32 v[46:47], v[34:35], v[244:245], v[46:47]
	v_pk_fma_f32 v[98:99], v[32:33], v[76:77], v[98:99]
	v_pk_fma_f32 v[252:253], v[32:33], v[246:247], v[252:253]
	v_pk_fma_f32 v[62:63], v[40:41], v[78:79], v[62:63]
	s_waitcnt lgkmcnt(10)
	v_pk_fma_f32 v[46:47], v[40:41], v[248:249], v[46:47]
	v_pk_fma_f32 v[98:99], v[42:43], v[80:81], v[98:99]
	v_pk_fma_f32 v[252:253], v[42:43], v[250:251], v[252:253]
	v_pk_add_f32 v[62:63], v[62:63], v[98:99]
	v_pk_add_f32 v[46:47], v[46:47], v[252:253]
	ds_read_b128 v[236:239], v65 offset:12288
	ds_read_b128 v[240:243], v65 offset:12304
	ds_read_b128 v[244:247], v65 offset:12320
	ds_read_b128 v[248:251], v65 offset:12336
	v_add_f32_e32 v62, v62, v63
	v_add_f32_e32 v46, v46, v47
	s_waitcnt lgkmcnt(13)
	v_pk_mul_f32 v[30:31], v[30:31], v[14:15] op_sel_hi:[1,0]
	v_pk_mul_f32 v[44:45], v[44:45], v[14:15] op_sel_hi:[1,0]
	v_add_f32_dpp v62, v62, v62 quad_perm:[1,0,3,2] row_mask:0xf bank_mask:0xf bound_ctrl:1
	v_add_f32_dpp v46, v46, v46 quad_perm:[1,0,3,2] row_mask:0xf bank_mask:0xf bound_ctrl:1
	v_pk_mul_f32 v[38:39], v[38:39], v[14:15] op_sel_hi:[1,0]
	v_pk_mul_f32 v[36:37], v[36:37], v[14:15] op_sel_hi:[1,0]
	v_add_f32_dpp v62, v62, v62 quad_perm:[2,3,0,1] row_mask:0xf bank_mask:0xf bound_ctrl:1
	v_add_f32_dpp v46, v46, v46 quad_perm:[2,3,0,1] row_mask:0xf bank_mask:0xf bound_ctrl:1
	v_pk_mul_f32 v[34:35], v[34:35], v[14:15] op_sel_hi:[1,0]
	v_pk_mul_f32 v[32:33], v[32:33], v[14:15] op_sel_hi:[1,0]
	v_add_f32_dpp v62, v62, v62 row_half_mirror row_mask:0xf bank_mask:0xf bound_ctrl:1
	v_add_f32_dpp v46, v46, v46 row_half_mirror row_mask:0xf bank_mask:0xf bound_ctrl:1
	v_pk_mul_f32 v[40:41], v[40:41], v[14:15] op_sel_hi:[1,0]
	v_pk_mul_f32 v[42:43], v[42:43], v[14:15] op_sel_hi:[1,0]
	s_waitcnt lgkmcnt(11)
	v_fma_f32 v63, -v14, v62, v58
	v_mul_f32_e32 v254, v8, v63
	global_store_dword v[28:29], v46, off offset:2048
	v_lshl_add_u64 v[28:29], v[28:29], 0, s[20:21]
	v_pk_fma_f32 v[30:31], v[66:67], v[254:255], v[30:31] op_sel_hi:[1,0,1]
	v_pk_fma_f32 v[44:45], v[68:69], v[254:255], v[44:45] op_sel_hi:[1,0,1]
	v_pk_fma_f32 v[38:39], v[70:71], v[254:255], v[38:39] op_sel_hi:[1,0,1]
	v_pk_fma_f32 v[36:37], v[72:73], v[254:255], v[36:37] op_sel_hi:[1,0,1]
	v_pk_fma_f32 v[34:35], v[74:75], v[254:255], v[34:35] op_sel_hi:[1,0,1]
	v_pk_fma_f32 v[32:33], v[76:77], v[254:255], v[32:33] op_sel_hi:[1,0,1]
	v_pk_fma_f32 v[40:41], v[78:79], v[254:255], v[40:41] op_sel_hi:[1,0,1]
	v_pk_fma_f32 v[42:43], v[80:81], v[254:255], v[42:43] op_sel_hi:[1,0,1]
	ds_read_b128 v[66:69], v65 offset:5120
	ds_read_b128 v[70:73], v65 offset:5136
	ds_read_b128 v[74:77], v65 offset:5152
	ds_read_b128 v[78:81], v65 offset:5168
	s_waitcnt lgkmcnt(11)
	v_pk_mul_f32 v[62:63], v[30:31], v[82:83]
	s_waitcnt lgkmcnt(7)
	v_pk_mul_f32 v[46:47], v[30:31], v[236:237]
	v_pk_mul_f32 v[98:99], v[44:45], v[84:85]
	v_pk_mul_f32 v[252:253], v[44:45], v[238:239]
	v_pk_fma_f32 v[62:63], v[38:39], v[86:87], v[62:63]
	s_waitcnt lgkmcnt(6)
	v_pk_fma_f32 v[46:47], v[38:39], v[240:241], v[46:47]
	v_pk_fma_f32 v[98:99], v[36:37], v[88:89], v[98:99]
	v_pk_fma_f32 v[252:253], v[36:37], v[242:243], v[252:253]
	v_pk_fma_f32 v[62:63], v[34:35], v[90:91], v[62:63]
	s_waitcnt lgkmcnt(5)
	v_pk_fma_f32 v[46:47], v[34:35], v[244:245], v[46:47]
	v_pk_fma_f32 v[98:99], v[32:33], v[92:93], v[98:99]
	v_pk_fma_f32 v[252:253], v[32:33], v[246:247], v[252:253]
	v_pk_fma_f32 v[62:63], v[40:41], v[94:95], v[62:63]
	s_waitcnt lgkmcnt(4)
	v_pk_fma_f32 v[46:47], v[40:41], v[248:249], v[46:47]
	v_pk_fma_f32 v[98:99], v[42:43], v[96:97], v[98:99]
	v_pk_fma_f32 v[252:253], v[42:43], v[250:251], v[252:253]
	v_pk_add_f32 v[62:63], v[62:63], v[98:99]
	v_pk_add_f32 v[46:47], v[46:47], v[252:253]
	ds_read_b128 v[236:239], v65 offset:12800
	ds_read_b128 v[240:243], v65 offset:12816
	ds_read_b128 v[244:247], v65 offset:12832
	ds_read_b128 v[248:251], v65 offset:12848
	v_add_f32_e32 v62, v62, v63
	v_add_f32_e32 v46, v46, v47
	v_pk_mul_f32 v[30:31], v[30:31], v[14:15] op_sel:[0,1]
	v_pk_mul_f32 v[44:45], v[44:45], v[14:15] op_sel:[0,1]
	v_add_f32_dpp v62, v62, v62 quad_perm:[1,0,3,2] row_mask:0xf bank_mask:0xf bound_ctrl:1
	v_add_f32_dpp v46, v46, v46 quad_perm:[1,0,3,2] row_mask:0xf bank_mask:0xf bound_ctrl:1
	v_pk_mul_f32 v[38:39], v[38:39], v[14:15] op_sel:[0,1]
	v_pk_mul_f32 v[36:37], v[36:37], v[14:15] op_sel:[0,1]
	v_add_f32_dpp v62, v62, v62 quad_perm:[2,3,0,1] row_mask:0xf bank_mask:0xf bound_ctrl:1
	v_add_f32_dpp v46, v46, v46 quad_perm:[2,3,0,1] row_mask:0xf bank_mask:0xf bound_ctrl:1
	v_pk_mul_f32 v[34:35], v[34:35], v[14:15] op_sel:[0,1]
	v_pk_mul_f32 v[32:33], v[32:33], v[14:15] op_sel:[0,1]
	v_add_f32_dpp v62, v62, v62 row_half_mirror row_mask:0xf bank_mask:0xf bound_ctrl:1
	v_add_f32_dpp v46, v46, v46 row_half_mirror row_mask:0xf bank_mask:0xf bound_ctrl:1
	v_pk_mul_f32 v[40:41], v[40:41], v[14:15] op_sel:[0,1]
	v_pk_mul_f32 v[42:43], v[42:43], v[14:15] op_sel:[0,1]
	v_fma_f32 v63, -v15, v62, v59
	v_mul_f32_e32 v254, v9, v63
	global_store_dword v[28:29], v46, off offset:-4096
	v_pk_fma_f32 v[30:31], v[82:83], v[254:255], v[30:31] op_sel_hi:[1,0,1]
	v_pk_fma_f32 v[44:45], v[84:85], v[254:255], v[44:45] op_sel_hi:[1,0,1]
	v_pk_fma_f32 v[38:39], v[86:87], v[254:255], v[38:39] op_sel_hi:[1,0,1]
	v_pk_fma_f32 v[36:37], v[88:89], v[254:255], v[36:37] op_sel_hi:[1,0,1]
	v_pk_fma_f32 v[34:35], v[90:91], v[254:255], v[34:35] op_sel_hi:[1,0,1]
	v_pk_fma_f32 v[32:33], v[92:93], v[254:255], v[32:33] op_sel_hi:[1,0,1]
	v_pk_fma_f32 v[40:41], v[94:95], v[254:255], v[40:41] op_sel_hi:[1,0,1]
	v_pk_fma_f32 v[42:43], v[96:97], v[254:255], v[42:43] op_sel_hi:[1,0,1]
	ds_read_b128 v[82:85], v65 offset:5632
	ds_read_b128 v[86:89], v65 offset:5648
	ds_read_b128 v[90:93], v65 offset:5664
	ds_read_b128 v[94:97], v65 offset:5680
	s_waitcnt lgkmcnt(11)
; __device__ __forceinline__ void delta_scan_task(KP p, int l, bool samp, int b, int h, int cgp, float* sm) {
;     ...
;         for (int s0 = 0; s0 < nst; s0 += 4) {
; #pragma unroll
;             for (int s4 = 0; s4 < 4; ++s4) {
;                 const int s = s0 + s4;
;                 f32x2 k2[8], q2[8];
; #pragma unroll
;                 for (int hh = 0; hh < 4; ++hh) {
;                     const float4 a = *(const float4*)(bufp + s * 128 + ks * 16 + hh * 4);
;                     const float4 c = *(const float4*)(bufp + 2048 + s * 128 + ks * 16 + hh * 4);
;                     k2[2 * hh] = (f32x2){a.x, a.y}; k2[2 * hh + 1] = (f32x2){a.z, a.w};
;                     q2[2 * hh] = (f32x2){c.x, c.y}; q2[2 * hh + 1] = (f32x2){c.z, c.w};
;                 }
;                 const float vv = bufp[4096 + s * 32 + wid * 8 + cc];
;                 const float beta = bufp[4608 + s], alpha = bufp[4624 + s];
;                 f32x2 d0 = S[0] * k2[0], d1v = S[1] * k2[1], d2 = S[2] * k2[2], d3 = S[3] * k2[3];
;                 d0 = S[4] * k2[4] + d0; d1v = S[5] * k2[5] + d1v; d2 = S[6] * k2[6] + d2; d3 = S[7] * k2[7] + d3;
;                 d0 = (d0 + d1v) + (d2 + d3);
;                 const f32x2 al2 = (f32x2){alpha, alpha};
;                 f32x2 sa[8];
; #pragma unroll
;                 for (int j = 0; j < 8; ++j) sa[j] = S[j] * al2;
;                 const float dk = red8(d0.x + d0.y);
;                 const float vn = beta * (vv - alpha * dk);
;                 const f32x2 vn2 = (f32x2){vn, vn};
; #pragma unroll
;                 for (int j = 0; j < 8; ++j) S[j] = k2[j] * vn2 + sa[j];
;                 f32x2 o0 = S[0] * q2[0], o1 = S[1] * q2[1], o2 = S[2] * q2[2], o3 = S[3] * q2[3];
;                 o0 = S[4] * q2[4] + o0; o1 = S[5] * q2[5] + o1; o2 = S[6] * q2[6] + o2; o3 = S[7] * q2[7] + o3;
;                 o0 = (o0 + o1) + (o2 + o3);
;                 const float o = red8(o0.x + o0.y);
;                 oraw[(size_t)(row0 + tile * 16 + s) * 512 + h * 128 + e] = o;
;             }
	v_pk_mul_f32 v[62:63], v[30:31], v[66:67]
	s_waitcnt lgkmcnt(7)
	v_pk_mul_f32 v[46:47], v[30:31], v[236:237]
	v_pk_mul_f32 v[98:99], v[44:45], v[68:69]
	v_pk_mul_f32 v[252:253], v[44:45], v[238:239]
	v_pk_fma_f32 v[62:63], v[38:39], v[70:71], v[62:63]
	s_waitcnt lgkmcnt(6)
	v_pk_fma_f32 v[46:47], v[38:39], v[240:241], v[46:47]
	v_pk_fma_f32 v[98:99], v[36:37], v[72:73], v[98:99]
	v_pk_fma_f32 v[252:253], v[36:37], v[242:243], v[252:253]
	v_pk_fma_f32 v[62:63], v[34:35], v[74:75], v[62:63]
	s_waitcnt lgkmcnt(5)
	v_pk_fma_f32 v[46:47], v[34:35], v[244:245], v[46:47]
	v_pk_fma_f32 v[98:99], v[32:33], v[76:77], v[98:99]
	v_pk_fma_f32 v[252:253], v[32:33], v[246:247], v[252:253]
	v_pk_fma_f32 v[62:63], v[40:41], v[78:79], v[62:63]
	s_waitcnt lgkmcnt(4)
	v_pk_fma_f32 v[46:47], v[40:41], v[248:249], v[46:47]
	v_pk_fma_f32 v[98:99], v[42:43], v[80:81], v[98:99]
	v_pk_fma_f32 v[252:253], v[42:43], v[250:251], v[252:253]
	v_pk_add_f32 v[62:63], v[62:63], v[98:99]
	v_pk_add_f32 v[46:47], v[46:47], v[252:253]
	ds_read_b128 v[236:239], v65 offset:13312
	ds_read_b128 v[240:243], v65 offset:13328
	ds_read_b128 v[244:247], v65 offset:13344
	ds_read_b128 v[248:251], v65 offset:13360
	v_add_f32_e32 v62, v62, v63
	v_add_f32_e32 v46, v46, v47
	v_pk_mul_f32 v[30:31], v[30:31], v[16:17] op_sel_hi:[1,0]
	v_pk_mul_f32 v[44:45], v[44:45], v[16:17] op_sel_hi:[1,0]
	v_add_f32_dpp v62, v62, v62 quad_perm:[1,0,3,2] row_mask:0xf bank_mask:0xf bound_ctrl:1
	v_add_f32_dpp v46, v46, v46 quad_perm:[1,0,3,2] row_mask:0xf bank_mask:0xf bound_ctrl:1
	v_pk_mul_f32 v[38:39], v[38:39], v[16:17] op_sel_hi:[1,0]
	v_pk_mul_f32 v[36:37], v[36:37], v[16:17] op_sel_hi:[1,0]
	v_add_f32_dpp v62, v62, v62 quad_perm:[2,3,0,1] row_mask:0xf bank_mask:0xf bound_ctrl:1
	v_add_f32_dpp v46, v46, v46 quad_perm:[2,3,0,1] row_mask:0xf bank_mask:0xf bound_ctrl:1
	v_pk_mul_f32 v[34:35], v[34:35], v[16:17] op_sel_hi:[1,0]
	v_pk_mul_f32 v[32:33], v[32:33], v[16:17] op_sel_hi:[1,0]
	v_add_f32_dpp v62, v62, v62 row_half_mirror row_mask:0xf bank_mask:0xf bound_ctrl:1
	v_add_f32_dpp v46, v46, v46 row_half_mirror row_mask:0xf bank_mask:0xf bound_ctrl:1
	v_pk_mul_f32 v[40:41], v[40:41], v[16:17] op_sel_hi:[1,0]
	v_pk_mul_f32 v[42:43], v[42:43], v[16:17] op_sel_hi:[1,0]
	v_fma_f32 v63, -v16, v62, v60
	v_mul_f32_e32 v254, v10, v63
	global_store_dword v[28:29], v46, off offset:-2048
	v_pk_fma_f32 v[30:31], v[66:67], v[254:255], v[30:31] op_sel_hi:[1,0,1]
	v_pk_fma_f32 v[44:45], v[68:69], v[254:255], v[44:45] op_sel_hi:[1,0,1]
	v_pk_fma_f32 v[38:39], v[70:71], v[254:255], v[38:39] op_sel_hi:[1,0,1]
	v_pk_fma_f32 v[36:37], v[72:73], v[254:255], v[36:37] op_sel_hi:[1,0,1]
	v_pk_fma_f32 v[34:35], v[74:75], v[254:255], v[34:35] op_sel_hi:[1,0,1]
	v_pk_fma_f32 v[32:33], v[76:77], v[254:255], v[32:33] op_sel_hi:[1,0,1]
	v_pk_fma_f32 v[40:41], v[78:79], v[254:255], v[40:41] op_sel_hi:[1,0,1]
	v_pk_fma_f32 v[42:43], v[80:81], v[254:255], v[42:43] op_sel_hi:[1,0,1]
	ds_read_b128 v[66:69], v65 offset:6144
	ds_read_b128 v[70:73], v65 offset:6160
	ds_read_b128 v[74:77], v65 offset:6176
	ds_read_b128 v[78:81], v65 offset:6192
	s_waitcnt lgkmcnt(11)
	v_pk_mul_f32 v[62:63], v[30:31], v[82:83]
	s_waitcnt lgkmcnt(7)
	v_pk_mul_f32 v[46:47], v[30:31], v[236:237]
	v_pk_mul_f32 v[98:99], v[44:45], v[84:85]
	v_pk_mul_f32 v[252:253], v[44:45], v[238:239]
	v_pk_fma_f32 v[62:63], v[38:39], v[86:87], v[62:63]
	s_waitcnt lgkmcnt(6)
	v_pk_fma_f32 v[46:47], v[38:39], v[240:241], v[46:47]
	v_pk_fma_f32 v[98:99], v[36:37], v[88:89], v[98:99]
	v_pk_fma_f32 v[252:253], v[36:37], v[242:243], v[252:253]
	v_pk_fma_f32 v[62:63], v[34:35], v[90:91], v[62:63]
	s_waitcnt lgkmcnt(5)
	v_pk_fma_f32 v[46:47], v[34:35], v[244:245], v[46:47]
	v_pk_fma_f32 v[98:99], v[32:33], v[92:93], v[98:99]
	v_pk_fma_f32 v[252:253], v[32:33], v[246:247], v[252:253]
	v_pk_fma_f32 v[62:63], v[40:41], v[94:95], v[62:63]
	s_waitcnt lgkmcnt(4)
	v_pk_fma_f32 v[46:47], v[40:41], v[248:249], v[46:47]
	v_pk_fma_f32 v[98:99], v[42:43], v[96:97], v[98:99]
	v_pk_fma_f32 v[252:253], v[42:43], v[250:251], v[252:253]
	v_pk_add_f32 v[62:63], v[62:63], v[98:99]
	v_pk_add_f32 v[46:47], v[46:47], v[252:253]
	ds_read_b128 v[236:239], v65 offset:13824
	ds_read_b128 v[240:243], v65 offset:13840
	ds_read_b128 v[244:247], v65 offset:13856
	ds_read_b128 v[248:251], v65 offset:13872
	v_add_f32_e32 v62, v62, v63
	v_add_f32_e32 v46, v46, v47
	v_pk_mul_f32 v[30:31], v[30:31], v[16:17] op_sel:[0,1]
	v_pk_mul_f32 v[44:45], v[44:45], v[16:17] op_sel:[0,1]
	v_add_f32_dpp v62, v62, v62 quad_perm:[1,0,3,2] row_mask:0xf bank_mask:0xf bound_ctrl:1
	v_add_f32_dpp v46, v46, v46 quad_perm:[1,0,3,2] row_mask:0xf bank_mask:0xf bound_ctrl:1
	v_pk_mul_f32 v[38:39], v[38:39], v[16:17] op_sel:[0,1]
	v_pk_mul_f32 v[36:37], v[36:37], v[16:17] op_sel:[0,1]
	v_add_f32_dpp v62, v62, v62 quad_perm:[2,3,0,1] row_mask:0xf bank_mask:0xf bound_ctrl:1
	v_add_f32_dpp v46, v46, v46 quad_perm:[2,3,0,1] row_mask:0xf bank_mask:0xf bound_ctrl:1
	v_pk_mul_f32 v[34:35], v[34:35], v[16:17] op_sel:[0,1]
	v_pk_mul_f32 v[32:33], v[32:33], v[16:17] op_sel:[0,1]
	v_add_f32_dpp v62, v62, v62 row_half_mirror row_mask:0xf bank_mask:0xf bound_ctrl:1
	v_add_f32_dpp v46, v46, v46 row_half_mirror row_mask:0xf bank_mask:0xf bound_ctrl:1
	v_pk_mul_f32 v[40:41], v[40:41], v[16:17] op_sel:[0,1]
	v_pk_mul_f32 v[42:43], v[42:43], v[16:17] op_sel:[0,1]
	v_fma_f32 v63, -v17, v62, v61
	v_mul_f32_e32 v254, v11, v63
	global_store_dword v[28:29], v46, off
	v_pk_fma_f32 v[30:31], v[82:83], v[254:255], v[30:31] op_sel_hi:[1,0,1]
	v_pk_fma_f32 v[44:45], v[84:85], v[254:255], v[44:45] op_sel_hi:[1,0,1]
	v_pk_fma_f32 v[38:39], v[86:87], v[254:255], v[38:39] op_sel_hi:[1,0,1]
	v_pk_fma_f32 v[36:37], v[88:89], v[254:255], v[36:37] op_sel_hi:[1,0,1]
	v_pk_fma_f32 v[34:35], v[90:91], v[254:255], v[34:35] op_sel_hi:[1,0,1]
	v_pk_fma_f32 v[32:33], v[92:93], v[254:255], v[32:33] op_sel_hi:[1,0,1]
	v_pk_fma_f32 v[40:41], v[94:95], v[254:255], v[40:41] op_sel_hi:[1,0,1]
	v_pk_fma_f32 v[42:43], v[96:97], v[254:255], v[42:43] op_sel_hi:[1,0,1]
	ds_read_b128 v[14:17], v234 offset:112
	ds_read_b128 v[8:11], v234 offset:48
	ds_read_b32 v58, v100 offset:1536
	ds_read_b32 v59, v100 offset:1664
	ds_read_b32 v60, v100 offset:1792
	ds_read_b32 v61, v100 offset:1920
	ds_read_b128 v[82:85], v65 offset:6656
	ds_read_b128 v[86:89], v65 offset:6672
	ds_read_b128 v[90:93], v65 offset:6688
	ds_read_b128 v[94:97], v65 offset:6704
	s_waitcnt lgkmcnt(15)
; __device__ __forceinline__ void delta_scan_task(KP p, int l, bool samp, int b, int h, int cgp, float* sm) {
;     ...
;         for (int s0 = 0; s0 < nst; s0 += 4) {
; #pragma unroll
;             for (int s4 = 0; s4 < 4; ++s4) {
;                 const int s = s0 + s4;
;                 f32x2 k2[8], q2[8];
; #pragma unroll
;                 for (int hh = 0; hh < 4; ++hh) {
;                     const float4 a = *(const float4*)(bufp + s * 128 + ks * 16 + hh * 4);
;                     const float4 c = *(const float4*)(bufp + 2048 + s * 128 + ks * 16 + hh * 4);
;                     k2[2 * hh] = (f32x2){a.x, a.y}; k2[2 * hh + 1] = (f32x2){a.z, a.w};
;                     q2[2 * hh] = (f32x2){c.x, c.y}; q2[2 * hh + 1] = (f32x2){c.z, c.w};
;                 }
;                 const float vv = bufp[4096 + s * 32 + wid * 8 + cc];
;                 const float beta = bufp[4608 + s], alpha = bufp[4624 + s];
;                 f32x2 d0 = S[0] * k2[0], d1v = S[1] * k2[1], d2 = S[2] * k2[2], d3 = S[3] * k2[3];
;                 d0 = S[4] * k2[4] + d0; d1v = S[5] * k2[5] + d1v; d2 = S[6] * k2[6] + d2; d3 = S[7] * k2[7] + d3;
;                 d0 = (d0 + d1v) + (d2 + d3);
;                 const f32x2 al2 = (f32x2){alpha, alpha};
;                 f32x2 sa[8];
; #pragma unroll
;                 for (int j = 0; j < 8; ++j) sa[j] = S[j] * al2;
;                 const float dk = red8(d0.x + d0.y);
;                 const float vn = beta * (vv - alpha * dk);
;                 const f32x2 vn2 = (f32x2){vn, vn};
; #pragma unroll
;                 for (int j = 0; j < 8; ++j) S[j] = k2[j] * vn2 + sa[j];
;                 f32x2 o0 = S[0] * q2[0], o1 = S[1] * q2[1], o2 = S[2] * q2[2], o3 = S[3] * q2[3];
;                 o0 = S[4] * q2[4] + o0; o1 = S[5] * q2[5] + o1; o2 = S[6] * q2[6] + o2; o3 = S[7] * q2[7] + o3;
;                 o0 = (o0 + o1) + (o2 + o3);
;                 const float o = red8(o0.x + o0.y);
;                 oraw[(size_t)(row0 + tile * 16 + s) * 512 + h * 128 + e] = o;
;             }
	v_pk_mul_f32 v[62:63], v[30:31], v[66:67]
	s_waitcnt lgkmcnt(13)
	v_pk_mul_f32 v[46:47], v[30:31], v[236:237]
	v_pk_mul_f32 v[98:99], v[44:45], v[68:69]
	v_pk_mul_f32 v[252:253], v[44:45], v[238:239]
	v_pk_fma_f32 v[62:63], v[38:39], v[70:71], v[62:63]
	s_waitcnt lgkmcnt(12)
	v_pk_fma_f32 v[46:47], v[38:39], v[240:241], v[46:47]
	v_pk_fma_f32 v[98:99], v[36:37], v[72:73], v[98:99]
	v_pk_fma_f32 v[252:253], v[36:37], v[242:243], v[252:253]
	v_pk_fma_f32 v[62:63], v[34:35], v[74:75], v[62:63]
	s_waitcnt lgkmcnt(11)
	v_pk_fma_f32 v[46:47], v[34:35], v[244:245], v[46:47]
	v_pk_fma_f32 v[98:99], v[32:33], v[76:77], v[98:99]
	v_pk_fma_f32 v[252:253], v[32:33], v[246:247], v[252:253]
	v_pk_fma_f32 v[62:63], v[40:41], v[78:79], v[62:63]
	s_waitcnt lgkmcnt(10)
	v_pk_fma_f32 v[46:47], v[40:41], v[248:249], v[46:47]
	v_pk_fma_f32 v[98:99], v[42:43], v[80:81], v[98:99]
	v_pk_fma_f32 v[252:253], v[42:43], v[250:251], v[252:253]
	v_pk_add_f32 v[62:63], v[62:63], v[98:99]
	v_pk_add_f32 v[46:47], v[46:47], v[252:253]
	ds_read_b128 v[236:239], v65 offset:14336
	ds_read_b128 v[240:243], v65 offset:14352
	ds_read_b128 v[244:247], v65 offset:14368
	ds_read_b128 v[248:251], v65 offset:14384
	v_add_f32_e32 v62, v62, v63
	v_add_f32_e32 v46, v46, v47
	s_waitcnt lgkmcnt(13)
	v_pk_mul_f32 v[30:31], v[30:31], v[14:15] op_sel_hi:[1,0]
	v_pk_mul_f32 v[44:45], v[44:45], v[14:15] op_sel_hi:[1,0]
	v_add_f32_dpp v62, v62, v62 quad_perm:[1,0,3,2] row_mask:0xf bank_mask:0xf bound_ctrl:1
	v_add_f32_dpp v46, v46, v46 quad_perm:[1,0,3,2] row_mask:0xf bank_mask:0xf bound_ctrl:1
	v_pk_mul_f32 v[38:39], v[38:39], v[14:15] op_sel_hi:[1,0]
	v_pk_mul_f32 v[36:37], v[36:37], v[14:15] op_sel_hi:[1,0]
	v_add_f32_dpp v62, v62, v62 quad_perm:[2,3,0,1] row_mask:0xf bank_mask:0xf bound_ctrl:1
	v_add_f32_dpp v46, v46, v46 quad_perm:[2,3,0,1] row_mask:0xf bank_mask:0xf bound_ctrl:1
	v_pk_mul_f32 v[34:35], v[34:35], v[14:15] op_sel_hi:[1,0]
	v_pk_mul_f32 v[32:33], v[32:33], v[14:15] op_sel_hi:[1,0]
	v_add_f32_dpp v62, v62, v62 row_half_mirror row_mask:0xf bank_mask:0xf bound_ctrl:1
	v_add_f32_dpp v46, v46, v46 row_half_mirror row_mask:0xf bank_mask:0xf bound_ctrl:1
	v_pk_mul_f32 v[40:41], v[40:41], v[14:15] op_sel_hi:[1,0]
	v_pk_mul_f32 v[42:43], v[42:43], v[14:15] op_sel_hi:[1,0]
	s_waitcnt lgkmcnt(11)
	v_fma_f32 v63, -v14, v62, v58
	v_mul_f32_e32 v254, v8, v63
	global_store_dword v[28:29], v46, off offset:2048
	v_lshl_add_u64 v[28:29], v[28:29], 0, s[20:21]
	v_pk_fma_f32 v[30:31], v[66:67], v[254:255], v[30:31] op_sel_hi:[1,0,1]
	v_pk_fma_f32 v[44:45], v[68:69], v[254:255], v[44:45] op_sel_hi:[1,0,1]
	v_pk_fma_f32 v[38:39], v[70:71], v[254:255], v[38:39] op_sel_hi:[1,0,1]
	v_pk_fma_f32 v[36:37], v[72:73], v[254:255], v[36:37] op_sel_hi:[1,0,1]
	v_pk_fma_f32 v[34:35], v[74:75], v[254:255], v[34:35] op_sel_hi:[1,0,1]
	v_pk_fma_f32 v[32:33], v[76:77], v[254:255], v[32:33] op_sel_hi:[1,0,1]
	v_pk_fma_f32 v[40:41], v[78:79], v[254:255], v[40:41] op_sel_hi:[1,0,1]
	v_pk_fma_f32 v[42:43], v[80:81], v[254:255], v[42:43] op_sel_hi:[1,0,1]
	ds_read_b128 v[66:69], v65 offset:7168
	ds_read_b128 v[70:73], v65 offset:7184
	ds_read_b128 v[74:77], v65 offset:7200
	ds_read_b128 v[78:81], v65 offset:7216
	s_waitcnt lgkmcnt(11)
	v_pk_mul_f32 v[62:63], v[30:31], v[82:83]
	s_waitcnt lgkmcnt(7)
	v_pk_mul_f32 v[46:47], v[30:31], v[236:237]
	v_pk_mul_f32 v[98:99], v[44:45], v[84:85]
	v_pk_mul_f32 v[252:253], v[44:45], v[238:239]
	v_pk_fma_f32 v[62:63], v[38:39], v[86:87], v[62:63]
	s_waitcnt lgkmcnt(6)
	v_pk_fma_f32 v[46:47], v[38:39], v[240:241], v[46:47]
	v_pk_fma_f32 v[98:99], v[36:37], v[88:89], v[98:99]
	v_pk_fma_f32 v[252:253], v[36:37], v[242:243], v[252:253]
	v_pk_fma_f32 v[62:63], v[34:35], v[90:91], v[62:63]
	s_waitcnt lgkmcnt(5)
	v_pk_fma_f32 v[46:47], v[34:35], v[244:245], v[46:47]
	v_pk_fma_f32 v[98:99], v[32:33], v[92:93], v[98:99]
	v_pk_fma_f32 v[252:253], v[32:33], v[246:247], v[252:253]
	v_pk_fma_f32 v[62:63], v[40:41], v[94:95], v[62:63]
	s_waitcnt lgkmcnt(4)
	v_pk_fma_f32 v[46:47], v[40:41], v[248:249], v[46:47]
	v_pk_fma_f32 v[98:99], v[42:43], v[96:97], v[98:99]
	v_pk_fma_f32 v[252:253], v[42:43], v[250:251], v[252:253]
	v_pk_add_f32 v[62:63], v[62:63], v[98:99]
	v_pk_add_f32 v[46:47], v[46:47], v[252:253]
	ds_read_b128 v[236:239], v65 offset:14848
	ds_read_b128 v[240:243], v65 offset:14864
	ds_read_b128 v[244:247], v65 offset:14880
	ds_read_b128 v[248:251], v65 offset:14896
	v_add_f32_e32 v62, v62, v63
	v_add_f32_e32 v46, v46, v47
	v_pk_mul_f32 v[30:31], v[30:31], v[14:15] op_sel:[0,1]
	v_pk_mul_f32 v[44:45], v[44:45], v[14:15] op_sel:[0,1]
	v_add_f32_dpp v62, v62, v62 quad_perm:[1,0,3,2] row_mask:0xf bank_mask:0xf bound_ctrl:1
	v_add_f32_dpp v46, v46, v46 quad_perm:[1,0,3,2] row_mask:0xf bank_mask:0xf bound_ctrl:1
	v_pk_mul_f32 v[38:39], v[38:39], v[14:15] op_sel:[0,1]
	v_pk_mul_f32 v[36:37], v[36:37], v[14:15] op_sel:[0,1]
	v_add_f32_dpp v62, v62, v62 quad_perm:[2,3,0,1] row_mask:0xf bank_mask:0xf bound_ctrl:1
	v_add_f32_dpp v46, v46, v46 quad_perm:[2,3,0,1] row_mask:0xf bank_mask:0xf bound_ctrl:1
	v_pk_mul_f32 v[34:35], v[34:35], v[14:15] op_sel:[0,1]
	v_pk_mul_f32 v[32:33], v[32:33], v[14:15] op_sel:[0,1]
	v_add_f32_dpp v62, v62, v62 row_half_mirror row_mask:0xf bank_mask:0xf bound_ctrl:1
	v_add_f32_dpp v46, v46, v46 row_half_mirror row_mask:0xf bank_mask:0xf bound_ctrl:1
	v_pk_mul_f32 v[40:41], v[40:41], v[14:15] op_sel:[0,1]
	v_pk_mul_f32 v[42:43], v[42:43], v[14:15] op_sel:[0,1]
	v_fma_f32 v63, -v15, v62, v59
	v_mul_f32_e32 v254, v9, v63
	global_store_dword v[28:29], v46, off offset:-4096
	v_pk_fma_f32 v[30:31], v[82:83], v[254:255], v[30:31] op_sel_hi:[1,0,1]
	v_pk_fma_f32 v[44:45], v[84:85], v[254:255], v[44:45] op_sel_hi:[1,0,1]
	v_pk_fma_f32 v[38:39], v[86:87], v[254:255], v[38:39] op_sel_hi:[1,0,1]
	v_pk_fma_f32 v[36:37], v[88:89], v[254:255], v[36:37] op_sel_hi:[1,0,1]
	v_pk_fma_f32 v[34:35], v[90:91], v[254:255], v[34:35] op_sel_hi:[1,0,1]
	v_pk_fma_f32 v[32:33], v[92:93], v[254:255], v[32:33] op_sel_hi:[1,0,1]
	v_pk_fma_f32 v[40:41], v[94:95], v[254:255], v[40:41] op_sel_hi:[1,0,1]
	v_pk_fma_f32 v[42:43], v[96:97], v[254:255], v[42:43] op_sel_hi:[1,0,1]
	ds_read_b128 v[82:85], v65 offset:7680
	ds_read_b128 v[86:89], v65 offset:7696
	ds_read_b128 v[90:93], v65 offset:7712
	ds_read_b128 v[94:97], v65 offset:7728
	s_waitcnt lgkmcnt(11)
; __device__ __forceinline__ void delta_scan_task(KP p, int l, bool samp, int b, int h, int cgp, float* sm) {
;     ...
;         for (int s0 = 0; s0 < nst; s0 += 4) {
; #pragma unroll
;             for (int s4 = 0; s4 < 4; ++s4) {
;                 const int s = s0 + s4;
;                 f32x2 k2[8], q2[8];
; #pragma unroll
;                 for (int hh = 0; hh < 4; ++hh) {
;                     const float4 a = *(const float4*)(bufp + s * 128 + ks * 16 + hh * 4);
;                     const float4 c = *(const float4*)(bufp + 2048 + s * 128 + ks * 16 + hh * 4);
;                     k2[2 * hh] = (f32x2){a.x, a.y}; k2[2 * hh + 1] = (f32x2){a.z, a.w};
;                     q2[2 * hh] = (f32x2){c.x, c.y}; q2[2 * hh + 1] = (f32x2){c.z, c.w};
;                 }
;                 const float vv = bufp[4096 + s * 32 + wid * 8 + cc];
;                 const float beta = bufp[4608 + s], alpha = bufp[4624 + s];
;                 f32x2 d0 = S[0] * k2[0], d1v = S[1] * k2[1], d2 = S[2] * k2[2], d3 = S[3] * k2[3];
;                 d0 = S[4] * k2[4] + d0; d1v = S[5] * k2[5] + d1v; d2 = S[6] * k2[6] + d2; d3 = S[7] * k2[7] + d3;
;                 d0 = (d0 + d1v) + (d2 + d3);
;                 const f32x2 al2 = (f32x2){alpha, alpha};
;                 f32x2 sa[8];
; #pragma unroll
;                 for (int j = 0; j < 8; ++j) sa[j] = S[j] * al2;
;                 const float dk = red8(d0.x + d0.y);
;                 const float vn = beta * (vv - alpha * dk);
;                 const f32x2 vn2 = (f32x2){vn, vn};
; #pragma unroll
;                 for (int j = 0; j < 8; ++j) S[j] = k2[j] * vn2 + sa[j];
;                 f32x2 o0 = S[0] * q2[0], o1 = S[1] * q2[1], o2 = S[2] * q2[2], o3 = S[3] * q2[3];
;                 o0 = S[4] * q2[4] + o0; o1 = S[5] * q2[5] + o1; o2 = S[6] * q2[6] + o2; o3 = S[7] * q2[7] + o3;
;                 o0 = (o0 + o1) + (o2 + o3);
;                 const float o = red8(o0.x + o0.y);
;                 oraw[(size_t)(row0 + tile * 16 + s) * 512 + h * 128 + e] = o;
;             }
	v_pk_mul_f32 v[62:63], v[30:31], v[66:67]
	s_waitcnt lgkmcnt(7)
	v_pk_mul_f32 v[46:47], v[30:31], v[236:237]
	v_pk_mul_f32 v[98:99], v[44:45], v[68:69]
	v_pk_mul_f32 v[252:253], v[44:45], v[238:239]
	v_pk_fma_f32 v[62:63], v[38:39], v[70:71], v[62:63]
	s_waitcnt lgkmcnt(6)
	v_pk_fma_f32 v[46:47], v[38:39], v[240:241], v[46:47]
	v_pk_fma_f32 v[98:99], v[36:37], v[72:73], v[98:99]
	v_pk_fma_f32 v[252:253], v[36:37], v[242:243], v[252:253]
	v_pk_fma_f32 v[62:63], v[34:35], v[74:75], v[62:63]
	s_waitcnt lgkmcnt(5)
	v_pk_fma_f32 v[46:47], v[34:35], v[244:245], v[46:47]
	v_pk_fma_f32 v[98:99], v[32:33], v[76:77], v[98:99]
	v_pk_fma_f32 v[252:253], v[32:33], v[246:247], v[252:253]
	v_pk_fma_f32 v[62:63], v[40:41], v[78:79], v[62:63]
	s_waitcnt lgkmcnt(4)
	v_pk_fma_f32 v[46:47], v[40:41], v[248:249], v[46:47]
	v_pk_fma_f32 v[98:99], v[42:43], v[80:81], v[98:99]
	v_pk_fma_f32 v[252:253], v[42:43], v[250:251], v[252:253]
	v_pk_add_f32 v[62:63], v[62:63], v[98:99]
	v_pk_add_f32 v[46:47], v[46:47], v[252:253]
	ds_read_b128 v[236:239], v65 offset:15360
	ds_read_b128 v[240:243], v65 offset:15376
	ds_read_b128 v[244:247], v65 offset:15392
	ds_read_b128 v[248:251], v65 offset:15408
	v_add_f32_e32 v62, v62, v63
	v_add_f32_e32 v46, v46, v47
	v_pk_mul_f32 v[30:31], v[30:31], v[16:17] op_sel_hi:[1,0]
	v_pk_mul_f32 v[44:45], v[44:45], v[16:17] op_sel_hi:[1,0]
	v_add_f32_dpp v62, v62, v62 quad_perm:[1,0,3,2] row_mask:0xf bank_mask:0xf bound_ctrl:1
	v_add_f32_dpp v46, v46, v46 quad_perm:[1,0,3,2] row_mask:0xf bank_mask:0xf bound_ctrl:1
	v_pk_mul_f32 v[38:39], v[38:39], v[16:17] op_sel_hi:[1,0]
	v_pk_mul_f32 v[36:37], v[36:37], v[16:17] op_sel_hi:[1,0]
	v_add_f32_dpp v62, v62, v62 quad_perm:[2,3,0,1] row_mask:0xf bank_mask:0xf bound_ctrl:1
	v_add_f32_dpp v46, v46, v46 quad_perm:[2,3,0,1] row_mask:0xf bank_mask:0xf bound_ctrl:1
	v_pk_mul_f32 v[34:35], v[34:35], v[16:17] op_sel_hi:[1,0]
	v_pk_mul_f32 v[32:33], v[32:33], v[16:17] op_sel_hi:[1,0]
	v_add_f32_dpp v62, v62, v62 row_half_mirror row_mask:0xf bank_mask:0xf bound_ctrl:1
	v_add_f32_dpp v46, v46, v46 row_half_mirror row_mask:0xf bank_mask:0xf bound_ctrl:1
	v_pk_mul_f32 v[40:41], v[40:41], v[16:17] op_sel_hi:[1,0]
	v_pk_mul_f32 v[42:43], v[42:43], v[16:17] op_sel_hi:[1,0]
	v_fma_f32 v63, -v16, v62, v60
	v_mul_f32_e32 v254, v10, v63
	global_store_dword v[28:29], v46, off offset:-2048
	v_pk_fma_f32 v[30:31], v[66:67], v[254:255], v[30:31] op_sel_hi:[1,0,1]
	v_pk_fma_f32 v[44:45], v[68:69], v[254:255], v[44:45] op_sel_hi:[1,0,1]
	v_pk_fma_f32 v[38:39], v[70:71], v[254:255], v[38:39] op_sel_hi:[1,0,1]
	v_pk_fma_f32 v[36:37], v[72:73], v[254:255], v[36:37] op_sel_hi:[1,0,1]
	v_pk_fma_f32 v[34:35], v[74:75], v[254:255], v[34:35] op_sel_hi:[1,0,1]
	v_pk_fma_f32 v[32:33], v[76:77], v[254:255], v[32:33] op_sel_hi:[1,0,1]
	v_pk_fma_f32 v[40:41], v[78:79], v[254:255], v[40:41] op_sel_hi:[1,0,1]
	v_pk_fma_f32 v[42:43], v[80:81], v[254:255], v[42:43] op_sel_hi:[1,0,1]
	s_waitcnt lgkmcnt(7)
	v_pk_mul_f32 v[62:63], v[30:31], v[82:83]
	s_waitcnt lgkmcnt(3)
	v_pk_mul_f32 v[46:47], v[30:31], v[236:237]
	v_pk_mul_f32 v[98:99], v[44:45], v[84:85]
	v_pk_mul_f32 v[252:253], v[44:45], v[238:239]
	v_pk_fma_f32 v[62:63], v[38:39], v[86:87], v[62:63]
	s_waitcnt lgkmcnt(2)
	v_pk_fma_f32 v[46:47], v[38:39], v[240:241], v[46:47]
	v_pk_fma_f32 v[98:99], v[36:37], v[88:89], v[98:99]
	v_pk_fma_f32 v[252:253], v[36:37], v[242:243], v[252:253]
	v_pk_fma_f32 v[62:63], v[34:35], v[90:91], v[62:63]
	s_waitcnt lgkmcnt(1)
	v_pk_fma_f32 v[46:47], v[34:35], v[244:245], v[46:47]
	v_pk_fma_f32 v[98:99], v[32:33], v[92:93], v[98:99]
	v_pk_fma_f32 v[252:253], v[32:33], v[246:247], v[252:253]
	v_pk_fma_f32 v[62:63], v[40:41], v[94:95], v[62:63]
	s_waitcnt lgkmcnt(0)
	v_pk_fma_f32 v[46:47], v[40:41], v[248:249], v[46:47]
	v_pk_fma_f32 v[98:99], v[42:43], v[96:97], v[98:99]
	v_pk_fma_f32 v[252:253], v[42:43], v[250:251], v[252:253]
	v_pk_add_f32 v[62:63], v[62:63], v[98:99]
	v_pk_add_f32 v[46:47], v[46:47], v[252:253]
	ds_read_b128 v[236:239], v65 offset:15872
	ds_read_b128 v[240:243], v65 offset:15888
	ds_read_b128 v[244:247], v65 offset:15904
	ds_read_b128 v[248:251], v65 offset:15920
	v_add_f32_e32 v62, v62, v63
	v_add_f32_e32 v46, v46, v47
	v_pk_mul_f32 v[30:31], v[30:31], v[16:17] op_sel:[0,1]
	v_pk_mul_f32 v[44:45], v[44:45], v[16:17] op_sel:[0,1]
	v_add_f32_dpp v62, v62, v62 quad_perm:[1,0,3,2] row_mask:0xf bank_mask:0xf bound_ctrl:1
	v_add_f32_dpp v46, v46, v46 quad_perm:[1,0,3,2] row_mask:0xf bank_mask:0xf bound_ctrl:1
	v_pk_mul_f32 v[38:39], v[38:39], v[16:17] op_sel:[0,1]
	v_pk_mul_f32 v[36:37], v[36:37], v[16:17] op_sel:[0,1]
	v_add_f32_dpp v62, v62, v62 quad_perm:[2,3,0,1] row_mask:0xf bank_mask:0xf bound_ctrl:1
	v_add_f32_dpp v46, v46, v46 quad_perm:[2,3,0,1] row_mask:0xf bank_mask:0xf bound_ctrl:1
	v_pk_mul_f32 v[34:35], v[34:35], v[16:17] op_sel:[0,1]
	v_pk_mul_f32 v[32:33], v[32:33], v[16:17] op_sel:[0,1]
	v_add_f32_dpp v62, v62, v62 row_half_mirror row_mask:0xf bank_mask:0xf bound_ctrl:1
	v_add_f32_dpp v46, v46, v46 row_half_mirror row_mask:0xf bank_mask:0xf bound_ctrl:1
	v_pk_mul_f32 v[40:41], v[40:41], v[16:17] op_sel:[0,1]
	v_pk_mul_f32 v[42:43], v[42:43], v[16:17] op_sel:[0,1]
	v_fma_f32 v63, -v17, v62, v61
	v_mul_f32_e32 v254, v11, v63
	global_store_dword v[28:29], v46, off
	v_pk_fma_f32 v[30:31], v[82:83], v[254:255], v[30:31] op_sel_hi:[1,0,1]
	v_pk_fma_f32 v[44:45], v[84:85], v[254:255], v[44:45] op_sel_hi:[1,0,1]
	v_pk_fma_f32 v[38:39], v[86:87], v[254:255], v[38:39] op_sel_hi:[1,0,1]
	v_pk_fma_f32 v[36:37], v[88:89], v[254:255], v[36:37] op_sel_hi:[1,0,1]
	v_pk_fma_f32 v[34:35], v[90:91], v[254:255], v[34:35] op_sel_hi:[1,0,1]
	v_pk_fma_f32 v[32:33], v[92:93], v[254:255], v[32:33] op_sel_hi:[1,0,1]
	v_pk_fma_f32 v[40:41], v[94:95], v[254:255], v[40:41] op_sel_hi:[1,0,1]
	v_pk_fma_f32 v[42:43], v[96:97], v[254:255], v[42:43] op_sel_hi:[1,0,1]
	s_waitcnt lgkmcnt(3)
	v_pk_mul_f32 v[46:47], v[30:31], v[236:237]
	v_pk_mul_f32 v[252:253], v[44:45], v[238:239]
	s_waitcnt lgkmcnt(2)
	v_pk_fma_f32 v[46:47], v[38:39], v[240:241], v[46:47]
	v_pk_fma_f32 v[252:253], v[36:37], v[242:243], v[252:253]
	s_waitcnt lgkmcnt(1)
	v_pk_fma_f32 v[46:47], v[34:35], v[244:245], v[46:47]
	v_pk_fma_f32 v[252:253], v[32:33], v[246:247], v[252:253]
	s_waitcnt lgkmcnt(0)
	v_pk_fma_f32 v[46:47], v[40:41], v[248:249], v[46:47]
	v_pk_fma_f32 v[252:253], v[42:43], v[250:251], v[252:253]
	s_nop 0
	v_pk_add_f32 v[46:47], v[46:47], v[252:253]
	s_nop 0
	v_add_f32_e32 v46, v46, v47
	s_nop 1
	v_add_f32_dpp v46, v46, v46 quad_perm:[1,0,3,2] row_mask:0xf bank_mask:0xf bound_ctrl:1
	s_nop 1
	v_add_f32_dpp v46, v46, v46 quad_perm:[2,3,0,1] row_mask:0xf bank_mask:0xf bound_ctrl:1
	s_nop 1
	v_add_f32_dpp v46, v46, v46 row_half_mirror row_mask:0xf bank_mask:0xf bound_ctrl:1
	global_store_dword v[28:29], v46, off offset:2048
	s_mov_b64 s[12:13], 0x8000
	v_lshl_add_u64 v[26:27], v[26:27], 0, s[12:13]
	s_cmpk_eq_i32 s42, 0x80
	s_mov_b32 s2, s42
	s_cbranch_scc0 .LBB0_139
; __device__ __forceinline__ void delta_scan_task(KP p, int l, bool samp, int b, int h, int cgp, float* sm) {
;     ...
;     float* so = (samp ? p->out + O_SDELTA : p->out + O_PDELTA) + sbase;
; #pragma unroll
;     for (int j = 0; j < 8; ++j) {
;         __builtin_nontemporal_store(S[j].x, so + (size_t)(ks * 16 + 2 * j) * 128 + e);
;         __builtin_nontemporal_store(S[j].y, so + (size_t)(ks * 16 + 2 * j + 1) * 128 + e);
;     }
;     __syncthreads();
	v_readlane_b32 s12, v230, 25
	s_lshl_b32 s2, s12, 5
	v_readlane_b32 s11, v233, 18
	v_readlane_b32 s13, v230, 26
	s_add_i32 s12, s2, s11
	s_ashr_i32 s13, s12, 31
	s_lshl_b64 s[12:13], s[12:13], 16
	s_add_u32 s12, s56, s12
	v_or_b32_e32 v0, v52, v51
	s_addc_u32 s13, s57, s13
	v_lshlrev_b32_e32 v2, 13, v19
	v_mov_b32_e32 v3, v13
	v_ashrrev_i32_e32 v1, 31, v0
	v_lshl_add_u64 v[2:3], s[12:13], 0, v[2:3]
	v_lshl_add_u64 v[0:1], v[0:1], 2, v[2:3]
	s_mov_b64 s[12:13], 0x4928000
	s_mov_b32 s2, 0x4929000
	v_lshl_add_u64 v[2:3], v[0:1], 0, s[12:13]
	v_add_co_u32_e32 v0, vcc, s2, v0
	s_mov_b64 s[12:13], 0
	s_nop 0
	v_addc_co_u32_e32 v1, vcc, 0, v1, vcc
	global_store_dword v[0:1], v30, off offset:-4096 nt
	global_store_dword v[2:3], v31, off offset:512 nt
	global_store_dword v[2:3], v44, off offset:1024 nt
	global_store_dword v[2:3], v45, off offset:1536 nt
	global_store_dword v[2:3], v38, off offset:2048 nt
	global_store_dword v[2:3], v39, off offset:2560 nt
	global_store_dword v[2:3], v36, off offset:3072 nt
	global_store_dword v[2:3], v37, off offset:3584 nt
	global_store_dword v[0:1], v34, off nt
	global_store_dword v[0:1], v35, off offset:512 nt
	global_store_dword v[0:1], v32, off offset:1024 nt
	global_store_dword v[0:1], v33, off offset:1536 nt
	global_store_dword v[0:1], v40, off offset:2048 nt
	global_store_dword v[0:1], v41, off offset:2560 nt
	global_store_dword v[0:1], v42, off offset:3072 nt
	global_store_dword v[0:1], v43, off offset:3584 nt
	s_setprio 0
	s_barrier
